# adds hand-written P2 idle-round weight conversion (dwordx4 loads, 3 items in flight per wave) to the previous stack
# baseline (speedup 1.0000x reference)
.LBB0_332:
	s_abs_i32 s0, s33
	s_waitcnt vmcnt(34)
	v_cvt_f32_u32_e32 v1, s0
	s_sub_i32 s1, 0, s0
	v_rcp_iflag_f32_e32 v1, v1
	s_nop 0
	v_mul_f32_e32 v1, 0x4f7ffffe, v1
	v_cvt_u32_f32_e32 v1, v1
	s_nop 0
	v_readfirstlane_b32 s3, v1
	s_mul_i32 s1, s1, s3
	s_mul_hi_u32 s1, s3, s1
	s_add_i32 s3, s3, s1
	s_mul_hi_u32 s1, s3, 0x480
	s_mul_i32 s1, s1, s0
	s_sub_i32 s1, 0x480, s1
	s_sub_i32 s3, s1, s0
	s_cmp_ge_u32 s1, s0
	s_cselect_b32 s1, s3, s1
	s_sub_i32 s3, s1, s0
	s_cmp_ge_u32 s1, s0
	s_cselect_b32 s10, s3, s1
	v_readlane_b32 s0, v254, 2
	s_sub_i32 s0, s0, s10
	s_cmp_lt_i32 s0, 0
	s_cbranch_scc1 .LBB0_376
	s_lshl_b32 s0, s0, 3
	s_add_i32 s0, s0, s78
	v_readlane_b32 s70, v254, 0
	v_readlane_b32 s71, v254, 1
	s_sub_u32 s70, s70, 0xc8
	s_subb_u32 s71, s71, 0
	s_load_dwordx4 s[4:7], s[70:71], 0x68
	s_load_dwordx2 s[8:9], s[70:71], 0x78
	s_load_dwordx2 s[10:11], s[70:71], 0x90
	s_add_u32 s12, s26, 0x2600000
	s_addc_u32 s13, s27, 0
	s_add_u32 s30, s26, 0x3200000
	s_addc_u32 s31, s27, 0
	s_add_u32 s42, s26, 0x3a00000
	s_addc_u32 s43, s27, 0
	v_and_b32_e32 v7, 63, v0
	v_lshrrev_b32_e32 v8, 3, v7
	v_and_b32_e32 v9, 7, v7
	v_lshlrev_b32_e32 v1, 13, v8
	v_lshl_add_u32 v1, v9, 4, v1
	v_mul_u32_u24_e32 v2, 0xb000, v8
	v_lshl_add_u32 v2, v9, 4, v2
	s_lshl_b32 s1, s78, 14
	v_mul_u32_u24_e32 v3, 33, v8
	v_lshl_add_u32 v3, v9, 2, v3
	v_lshl_add_u32 v3, v3, 2, s1
	v_mul_u32_u24_e32 v4, 0x108, v9
	v_add_u32_e32 v4, v4, v8
	v_lshl_add_u32 v4, v4, 2, s1
	v_mul_u32_u24_e32 v5, 0x1800, v8
	v_lshl_add_u32 v5, v9, 4, v5
	v_lshlrev_b32_e32 v6, 12, v8
	v_lshl_add_u32 v6, v9, 4, v6
	s_waitcnt lgkmcnt(0)
	s_mov_b32 s3, s0
	s_lshr_b32 s29, s3, 6
	s_and_b32 s35, s3, 63
	s_lshl_b32 s58, s29, 19
	s_lshl_b32 s59, s35, 7
	s_add_u32 s58, s58, s59
	s_add_u32 s46, s4, s58
	s_addc_u32 s47, s5, 0
	global_load_dwordx4 v[16:19], v1, s[46:47] nt
	v_add_u32_e32 v7, 0x10000, v1
	global_load_dwordx4 v[20:23], v7, s[46:47] nt
	v_add_u32_e32 v7, 0x20000, v1
	global_load_dwordx4 v[24:27], v7, s[46:47] nt
	v_add_u32_e32 v7, 0x30000, v1
	global_load_dwordx4 v[28:31], v7, s[46:47] nt
	v_add_u32_e32 v7, 0x40000, v1
	global_load_dwordx4 v[32:35], v7, s[46:47] nt
	v_add_u32_e32 v7, 0x50000, v1
	global_load_dwordx4 v[36:39], v7, s[46:47] nt
	v_add_u32_e32 v7, 0x60000, v1
	global_load_dwordx4 v[40:43], v7, s[46:47] nt
	v_add_u32_e32 v7, 0x70000, v1
	global_load_dwordx4 v[44:47], v7, s[46:47] nt
	s_add_i32 s3, s0, 1024
	s_lshr_b32 s29, s3, 6
	s_and_b32 s35, s3, 63
	s_lshl_b32 s58, s29, 19
	s_lshl_b32 s59, s35, 7
	s_add_u32 s58, s58, s59
	s_add_u32 s46, s4, s58
	s_addc_u32 s47, s5, 0
	global_load_dwordx4 v[48:51], v1, s[46:47] nt
	v_add_u32_e32 v7, 0x10000, v1
	global_load_dwordx4 v[52:55], v7, s[46:47] nt
	v_add_u32_e32 v7, 0x20000, v1
	global_load_dwordx4 v[56:59], v7, s[46:47] nt
	v_add_u32_e32 v7, 0x30000, v1
	global_load_dwordx4 v[60:63], v7, s[46:47] nt
	v_add_u32_e32 v7, 0x40000, v1
	global_load_dwordx4 v[64:67], v7, s[46:47] nt
	v_add_u32_e32 v7, 0x50000, v1
	global_load_dwordx4 v[68:71], v7, s[46:47] nt
	v_add_u32_e32 v7, 0x60000, v1
	global_load_dwordx4 v[72:75], v7, s[46:47] nt
	v_add_u32_e32 v7, 0x70000, v1
	global_load_dwordx4 v[76:79], v7, s[46:47] nt
	s_mov_b32 s3, s0
	s_lshr_b32 s29, s3, 6
	s_and_b32 s35, s3, 63
	s_lshl_b32 s58, s29, 19
	s_lshl_b32 s59, s35, 7
	s_add_u32 s58, s58, s59
	s_add_u32 s46, s6, s58
	s_addc_u32 s47, s7, 0
	global_load_dwordx4 v[80:83], v1, s[46:47] nt
	v_add_u32_e32 v7, 0x10000, v1
	global_load_dwordx4 v[84:87], v7, s[46:47] nt
	v_add_u32_e32 v7, 0x20000, v1
	global_load_dwordx4 v[88:91], v7, s[46:47] nt
	v_add_u32_e32 v7, 0x30000, v1
	global_load_dwordx4 v[92:95], v7, s[46:47] nt
	v_add_u32_e32 v7, 0x40000, v1
	global_load_dwordx4 v[96:99], v7, s[46:47] nt
	v_add_u32_e32 v7, 0x50000, v1
	global_load_dwordx4 v[100:103], v7, s[46:47] nt
	v_add_u32_e32 v7, 0x60000, v1
	global_load_dwordx4 v[104:107], v7, s[46:47] nt
	v_add_u32_e32 v7, 0x70000, v1
	global_load_dwordx4 v[108:111], v7, s[46:47] nt
	s_waitcnt vmcnt(16)
	ds_write_b32 v3, v16
	ds_write_b32 v3, v17 offset:4
	ds_write_b32 v3, v18 offset:8
	ds_write_b32 v3, v19 offset:12
	ds_write_b32 v3, v20 offset:1056
	ds_write_b32 v3, v21 offset:1060
	ds_write_b32 v3, v22 offset:1064
	ds_write_b32 v3, v23 offset:1068
	ds_write_b32 v3, v24 offset:2112
	ds_write_b32 v3, v25 offset:2116
	ds_write_b32 v3, v26 offset:2120
	ds_write_b32 v3, v27 offset:2124
	ds_write_b32 v3, v28 offset:3168
	ds_write_b32 v3, v29 offset:3172
	ds_write_b32 v3, v30 offset:3176
	ds_write_b32 v3, v31 offset:3180
	ds_write_b32 v3, v32 offset:4224
	ds_write_b32 v3, v33 offset:4228
	ds_write_b32 v3, v34 offset:4232
	ds_write_b32 v3, v35 offset:4236
	ds_write_b32 v3, v36 offset:5280
	ds_write_b32 v3, v37 offset:5284
	ds_write_b32 v3, v38 offset:5288
	ds_write_b32 v3, v39 offset:5292
	ds_write_b32 v3, v40 offset:6336
	ds_write_b32 v3, v41 offset:6340
	ds_write_b32 v3, v42 offset:6344
	ds_write_b32 v3, v43 offset:6348
	ds_write_b32 v3, v44 offset:7392
	ds_write_b32 v3, v45 offset:7396
	ds_write_b32 v3, v46 offset:7400
	ds_write_b32 v3, v47 offset:7404
	s_waitcnt lgkmcnt(0)
	s_mov_b32 s3, s0
	s_lshr_b32 s29, s3, 6
	s_and_b32 s35, s3, 63
	s_mul_i32 s58, s35, 0x30000
	s_lshl_b32 s59, s29, 7
	s_add_u32 s58, s58, s59
	s_add_u32 s48, s12, s58
	s_addc_u32 s49, s13, 0
	ds_read2_b32 v[8:9], v4 offset0:0 offset1:33
	ds_read2_b32 v[10:11], v4 offset0:66 offset1:99
	ds_read2_b32 v[12:13], v4 offset0:132 offset1:165
	ds_read2_b32 v[14:15], v4 offset0:198 offset1:231
	s_waitcnt lgkmcnt(0)
	v_cvt_pk_bf16_f32 v16, v8, v9
	v_cvt_pk_bf16_f32 v17, v10, v11
	v_cvt_pk_bf16_f32 v18, v12, v13
	v_cvt_pk_bf16_f32 v19, v14, v15
	global_store_dwordx4 v5, v[16:19], s[48:49]
	ds_read2_b32 v[8:9], v4 offset0:8 offset1:41
	ds_read2_b32 v[10:11], v4 offset0:74 offset1:107
	ds_read2_b32 v[12:13], v4 offset0:140 offset1:173
	ds_read2_b32 v[14:15], v4 offset0:206 offset1:239
	s_waitcnt lgkmcnt(0)
	v_cvt_pk_bf16_f32 v20, v8, v9
	v_cvt_pk_bf16_f32 v21, v10, v11
	v_cvt_pk_bf16_f32 v22, v12, v13
	v_cvt_pk_bf16_f32 v23, v14, v15
	v_add_u32_e32 v7, 0xc000, v5
	global_store_dwordx4 v7, v[20:23], s[48:49]
	ds_read2_b32 v[8:9], v4 offset0:16 offset1:49
	ds_read2_b32 v[10:11], v4 offset0:82 offset1:115
	ds_read2_b32 v[12:13], v4 offset0:148 offset1:181
	ds_read2_b32 v[14:15], v4 offset0:214 offset1:247
	s_waitcnt lgkmcnt(0)
	v_cvt_pk_bf16_f32 v24, v8, v9
	v_cvt_pk_bf16_f32 v25, v10, v11
	v_cvt_pk_bf16_f32 v26, v12, v13
	v_cvt_pk_bf16_f32 v27, v14, v15
	v_add_u32_e32 v7, 0x18000, v5
	global_store_dwordx4 v7, v[24:27], s[48:49]
	ds_read2_b32 v[8:9], v4 offset0:24 offset1:57
	ds_read2_b32 v[10:11], v4 offset0:90 offset1:123
	ds_read2_b32 v[12:13], v4 offset0:156 offset1:189
	ds_read2_b32 v[14:15], v4 offset0:222 offset1:255
	s_waitcnt lgkmcnt(0)
	v_cvt_pk_bf16_f32 v28, v8, v9
	v_cvt_pk_bf16_f32 v29, v10, v11
	v_cvt_pk_bf16_f32 v30, v12, v13
	v_cvt_pk_bf16_f32 v31, v14, v15
	v_add_u32_e32 v7, 0x24000, v5
	global_store_dwordx4 v7, v[28:31], s[48:49]
	s_mov_b32 s3, s0
	s_lshr_b32 s29, s3, 6
	s_and_b32 s35, s3, 63
	s_lshl_b32 s58, s29, 19
	s_lshl_b32 s59, s35, 7
	s_add_u32 s58, s58, s59
	s_add_u32 s46, s8, s58
	s_addc_u32 s47, s9, 0
	global_load_dwordx4 v[16:19], v1, s[46:47] nt
	v_add_u32_e32 v7, 0x10000, v1
	global_load_dwordx4 v[20:23], v7, s[46:47] nt
	v_add_u32_e32 v7, 0x20000, v1
	global_load_dwordx4 v[24:27], v7, s[46:47] nt
	v_add_u32_e32 v7, 0x30000, v1
	global_load_dwordx4 v[28:31], v7, s[46:47] nt
	v_add_u32_e32 v7, 0x40000, v1
	global_load_dwordx4 v[32:35], v7, s[46:47] nt
	v_add_u32_e32 v7, 0x50000, v1
	global_load_dwordx4 v[36:39], v7, s[46:47] nt
	v_add_u32_e32 v7, 0x60000, v1
	global_load_dwordx4 v[40:43], v7, s[46:47] nt
	v_add_u32_e32 v7, 0x70000, v1
	global_load_dwordx4 v[44:47], v7, s[46:47] nt
	s_waitcnt vmcnt(20)
	ds_write_b32 v3, v48
	ds_write_b32 v3, v49 offset:4
	ds_write_b32 v3, v50 offset:8
	ds_write_b32 v3, v51 offset:12
	ds_write_b32 v3, v52 offset:1056
	ds_write_b32 v3, v53 offset:1060
	ds_write_b32 v3, v54 offset:1064
	ds_write_b32 v3, v55 offset:1068
	ds_write_b32 v3, v56 offset:2112
	ds_write_b32 v3, v57 offset:2116
	ds_write_b32 v3, v58 offset:2120
	ds_write_b32 v3, v59 offset:2124
	ds_write_b32 v3, v60 offset:3168
	ds_write_b32 v3, v61 offset:3172
	ds_write_b32 v3, v62 offset:3176
	ds_write_b32 v3, v63 offset:3180
	ds_write_b32 v3, v64 offset:4224
	ds_write_b32 v3, v65 offset:4228
	ds_write_b32 v3, v66 offset:4232
	ds_write_b32 v3, v67 offset:4236
	ds_write_b32 v3, v68 offset:5280
	ds_write_b32 v3, v69 offset:5284
	ds_write_b32 v3, v70 offset:5288
	ds_write_b32 v3, v71 offset:5292
	ds_write_b32 v3, v72 offset:6336
	ds_write_b32 v3, v73 offset:6340
	ds_write_b32 v3, v74 offset:6344
	ds_write_b32 v3, v75 offset:6348
	ds_write_b32 v3, v76 offset:7392
	ds_write_b32 v3, v77 offset:7396
	ds_write_b32 v3, v78 offset:7400
	ds_write_b32 v3, v79 offset:7404
	s_waitcnt lgkmcnt(0)
	s_add_i32 s3, s0, 1024
	s_lshr_b32 s29, s3, 6
	s_and_b32 s35, s3, 63
	s_mul_i32 s58, s35, 0x30000
	s_lshl_b32 s59, s29, 7
	s_add_u32 s58, s58, s59
	s_add_u32 s48, s12, s58
	s_addc_u32 s49, s13, 0
	ds_read2_b32 v[8:9], v4 offset0:0 offset1:33
	ds_read2_b32 v[10:11], v4 offset0:66 offset1:99
	ds_read2_b32 v[12:13], v4 offset0:132 offset1:165
	ds_read2_b32 v[14:15], v4 offset0:198 offset1:231
	s_waitcnt lgkmcnt(0)
	v_cvt_pk_bf16_f32 v48, v8, v9
	v_cvt_pk_bf16_f32 v49, v10, v11
	v_cvt_pk_bf16_f32 v50, v12, v13
	v_cvt_pk_bf16_f32 v51, v14, v15
	global_store_dwordx4 v5, v[48:51], s[48:49]
	ds_read2_b32 v[8:9], v4 offset0:8 offset1:41
	ds_read2_b32 v[10:11], v4 offset0:74 offset1:107
	ds_read2_b32 v[12:13], v4 offset0:140 offset1:173
	ds_read2_b32 v[14:15], v4 offset0:206 offset1:239
	s_waitcnt lgkmcnt(0)
	v_cvt_pk_bf16_f32 v52, v8, v9
	v_cvt_pk_bf16_f32 v53, v10, v11
	v_cvt_pk_bf16_f32 v54, v12, v13
	v_cvt_pk_bf16_f32 v55, v14, v15
	v_add_u32_e32 v7, 0xc000, v5
	global_store_dwordx4 v7, v[52:55], s[48:49]
	ds_read2_b32 v[8:9], v4 offset0:16 offset1:49
	ds_read2_b32 v[10:11], v4 offset0:82 offset1:115
	ds_read2_b32 v[12:13], v4 offset0:148 offset1:181
	ds_read2_b32 v[14:15], v4 offset0:214 offset1:247
	s_waitcnt lgkmcnt(0)
	v_cvt_pk_bf16_f32 v56, v8, v9
	v_cvt_pk_bf16_f32 v57, v10, v11
	v_cvt_pk_bf16_f32 v58, v12, v13
	v_cvt_pk_bf16_f32 v59, v14, v15
	v_add_u32_e32 v7, 0x18000, v5
	global_store_dwordx4 v7, v[56:59], s[48:49]
	ds_read2_b32 v[8:9], v4 offset0:24 offset1:57
	ds_read2_b32 v[10:11], v4 offset0:90 offset1:123
	ds_read2_b32 v[12:13], v4 offset0:156 offset1:189
	ds_read2_b32 v[14:15], v4 offset0:222 offset1:255
	s_waitcnt lgkmcnt(0)
	v_cvt_pk_bf16_f32 v60, v8, v9
	v_cvt_pk_bf16_f32 v61, v10, v11
	v_cvt_pk_bf16_f32 v62, v12, v13
	v_cvt_pk_bf16_f32 v63, v14, v15
	v_add_u32_e32 v7, 0x24000, v5
	global_store_dwordx4 v7, v[60:63], s[48:49]
	s_add_i32 s3, s0, 1024
	s_lshr_b32 s29, s3, 6
	s_and_b32 s35, s3, 63
	s_lshl_b32 s58, s29, 19
	s_lshl_b32 s59, s35, 7
	s_add_u32 s58, s58, s59
	s_add_u32 s46, s8, s58
	s_addc_u32 s47, s9, 0
	global_load_dwordx4 v[48:51], v1, s[46:47] nt
	v_add_u32_e32 v7, 0x10000, v1
	global_load_dwordx4 v[52:55], v7, s[46:47] nt
	v_add_u32_e32 v7, 0x20000, v1
	global_load_dwordx4 v[56:59], v7, s[46:47] nt
	v_add_u32_e32 v7, 0x30000, v1
	global_load_dwordx4 v[60:63], v7, s[46:47] nt
	v_add_u32_e32 v7, 0x40000, v1
	global_load_dwordx4 v[64:67], v7, s[46:47] nt
	v_add_u32_e32 v7, 0x50000, v1
	global_load_dwordx4 v[68:71], v7, s[46:47] nt
	v_add_u32_e32 v7, 0x60000, v1
	global_load_dwordx4 v[72:75], v7, s[46:47] nt
	v_add_u32_e32 v7, 0x70000, v1
	global_load_dwordx4 v[76:79], v7, s[46:47] nt
	s_waitcnt vmcnt(24)
	ds_write_b32 v3, v80
	ds_write_b32 v3, v81 offset:4
	ds_write_b32 v3, v82 offset:8
	ds_write_b32 v3, v83 offset:12
	ds_write_b32 v3, v84 offset:1056
	ds_write_b32 v3, v85 offset:1060
	ds_write_b32 v3, v86 offset:1064
	ds_write_b32 v3, v87 offset:1068
	ds_write_b32 v3, v88 offset:2112
	ds_write_b32 v3, v89 offset:2116
	ds_write_b32 v3, v90 offset:2120
	ds_write_b32 v3, v91 offset:2124
	ds_write_b32 v3, v92 offset:3168
	ds_write_b32 v3, v93 offset:3172
	ds_write_b32 v3, v94 offset:3176
	ds_write_b32 v3, v95 offset:3180
	ds_write_b32 v3, v96 offset:4224
	ds_write_b32 v3, v97 offset:4228
	ds_write_b32 v3, v98 offset:4232
	ds_write_b32 v3, v99 offset:4236
	ds_write_b32 v3, v100 offset:5280
	ds_write_b32 v3, v101 offset:5284
	ds_write_b32 v3, v102 offset:5288
	ds_write_b32 v3, v103 offset:5292
	ds_write_b32 v3, v104 offset:6336
	ds_write_b32 v3, v105 offset:6340
	ds_write_b32 v3, v106 offset:6344
	ds_write_b32 v3, v107 offset:6348
	ds_write_b32 v3, v108 offset:7392
	ds_write_b32 v3, v109 offset:7396
	ds_write_b32 v3, v110 offset:7400
	ds_write_b32 v3, v111 offset:7404
	s_waitcnt lgkmcnt(0)
	s_mov_b32 s3, s0
	s_lshr_b32 s29, s3, 6
	s_and_b32 s35, s3, 63
	s_mul_i32 s58, s35, 0x30000
	s_lshl_b32 s59, s29, 7
	s_add_u32 s58, s58, s59
	s_add_u32 s58, s58, 0x1000
	s_add_u32 s48, s12, s58
	s_addc_u32 s49, s13, 0
	ds_read2_b32 v[8:9], v4 offset0:0 offset1:33
	ds_read2_b32 v[10:11], v4 offset0:66 offset1:99
	ds_read2_b32 v[12:13], v4 offset0:132 offset1:165
	ds_read2_b32 v[14:15], v4 offset0:198 offset1:231
	s_waitcnt lgkmcnt(0)
	v_cvt_pk_bf16_f32 v80, v8, v9
	v_cvt_pk_bf16_f32 v81, v10, v11
	v_cvt_pk_bf16_f32 v82, v12, v13
	v_cvt_pk_bf16_f32 v83, v14, v15
	global_store_dwordx4 v5, v[80:83], s[48:49]
	ds_read2_b32 v[8:9], v4 offset0:8 offset1:41
	ds_read2_b32 v[10:11], v4 offset0:74 offset1:107
	ds_read2_b32 v[12:13], v4 offset0:140 offset1:173
	ds_read2_b32 v[14:15], v4 offset0:206 offset1:239
	s_waitcnt lgkmcnt(0)
	v_cvt_pk_bf16_f32 v84, v8, v9
	v_cvt_pk_bf16_f32 v85, v10, v11
	v_cvt_pk_bf16_f32 v86, v12, v13
	v_cvt_pk_bf16_f32 v87, v14, v15
	v_add_u32_e32 v7, 0xc000, v5
	global_store_dwordx4 v7, v[84:87], s[48:49]
	ds_read2_b32 v[8:9], v4 offset0:16 offset1:49
	ds_read2_b32 v[10:11], v4 offset0:82 offset1:115
	ds_read2_b32 v[12:13], v4 offset0:148 offset1:181
	ds_read2_b32 v[14:15], v4 offset0:214 offset1:247
	s_waitcnt lgkmcnt(0)
	v_cvt_pk_bf16_f32 v88, v8, v9
	v_cvt_pk_bf16_f32 v89, v10, v11
	v_cvt_pk_bf16_f32 v90, v12, v13
	v_cvt_pk_bf16_f32 v91, v14, v15
	v_add_u32_e32 v7, 0x18000, v5
	global_store_dwordx4 v7, v[88:91], s[48:49]
	ds_read2_b32 v[8:9], v4 offset0:24 offset1:57
	ds_read2_b32 v[10:11], v4 offset0:90 offset1:123
	ds_read2_b32 v[12:13], v4 offset0:156 offset1:189
	ds_read2_b32 v[14:15], v4 offset0:222 offset1:255
	s_waitcnt lgkmcnt(0)
	v_cvt_pk_bf16_f32 v92, v8, v9
	v_cvt_pk_bf16_f32 v93, v10, v11
	v_cvt_pk_bf16_f32 v94, v12, v13
	v_cvt_pk_bf16_f32 v95, v14, v15
	v_add_u32_e32 v7, 0x24000, v5
	global_store_dwordx4 v7, v[92:95], s[48:49]
	s_mov_b32 s3, s0
	s_mul_i32 s29, s3, 0x1745e
	s_lshr_b32 s29, s29, 25
	s_mul_i32 s35, s29, 0x160
	s_sub_i32 s35, s3, s35
	s_mul_i32 s58, s29, 0x2c0000
	s_lshl_b32 s59, s35, 7
	s_add_u32 s58, s58, s59
	s_add_u32 s46, s10, s58
	s_addc_u32 s47, s11, 0
	global_load_dwordx4 v[80:83], v2, s[46:47] nt
	v_add_u32_e32 v7, 0x58000, v2
	global_load_dwordx4 v[84:87], v7, s[46:47] nt
	v_add_u32_e32 v7, 0xb0000, v2
	global_load_dwordx4 v[88:91], v7, s[46:47] nt
	v_add_u32_e32 v7, 0x108000, v2
	global_load_dwordx4 v[92:95], v7, s[46:47] nt
	v_add_u32_e32 v7, 0x160000, v2
	global_load_dwordx4 v[96:99], v7, s[46:47] nt
	v_add_u32_e32 v7, 0x1b8000, v2
	global_load_dwordx4 v[100:103], v7, s[46:47] nt
	v_add_u32_e32 v7, 0x210000, v2
	global_load_dwordx4 v[104:107], v7, s[46:47] nt
	v_add_u32_e32 v7, 0x268000, v2
	global_load_dwordx4 v[108:111], v7, s[46:47] nt
	s_waitcnt vmcnt(24)
	ds_write_b32 v3, v16
	ds_write_b32 v3, v17 offset:4
	ds_write_b32 v3, v18 offset:8
	ds_write_b32 v3, v19 offset:12
	ds_write_b32 v3, v20 offset:1056
	ds_write_b32 v3, v21 offset:1060
	ds_write_b32 v3, v22 offset:1064
	ds_write_b32 v3, v23 offset:1068
	ds_write_b32 v3, v24 offset:2112
	ds_write_b32 v3, v25 offset:2116
	ds_write_b32 v3, v26 offset:2120
	ds_write_b32 v3, v27 offset:2124
	ds_write_b32 v3, v28 offset:3168
	ds_write_b32 v3, v29 offset:3172
	ds_write_b32 v3, v30 offset:3176
	ds_write_b32 v3, v31 offset:3180
	ds_write_b32 v3, v32 offset:4224
	ds_write_b32 v3, v33 offset:4228
	ds_write_b32 v3, v34 offset:4232
	ds_write_b32 v3, v35 offset:4236
	ds_write_b32 v3, v36 offset:5280
	ds_write_b32 v3, v37 offset:5284
	ds_write_b32 v3, v38 offset:5288
	ds_write_b32 v3, v39 offset:5292
	ds_write_b32 v3, v40 offset:6336
	ds_write_b32 v3, v41 offset:6340
	ds_write_b32 v3, v42 offset:6344
	ds_write_b32 v3, v43 offset:6348
	ds_write_b32 v3, v44 offset:7392
	ds_write_b32 v3, v45 offset:7396
	ds_write_b32 v3, v46 offset:7400
	ds_write_b32 v3, v47 offset:7404
	s_waitcnt lgkmcnt(0)
	s_mov_b32 s3, s0
	s_lshr_b32 s29, s3, 6
	s_and_b32 s35, s3, 63
	s_lshl_b32 s58, s35, 17
	s_lshl_b32 s59, s29, 7
	s_add_u32 s58, s58, s59
	s_add_u32 s48, s30, s58
	s_addc_u32 s49, s31, 0
	ds_read2_b32 v[8:9], v4 offset0:0 offset1:33
	ds_read2_b32 v[10:11], v4 offset0:66 offset1:99
	ds_read2_b32 v[12:13], v4 offset0:132 offset1:165
	ds_read2_b32 v[14:15], v4 offset0:198 offset1:231
	s_waitcnt lgkmcnt(0)
	v_cvt_pk_bf16_f32 v16, v8, v9
	v_cvt_pk_bf16_f32 v17, v10, v11
	v_cvt_pk_bf16_f32 v18, v12, v13
	v_cvt_pk_bf16_f32 v19, v14, v15
	global_store_dwordx4 v6, v[16:19], s[48:49]
	ds_read2_b32 v[8:9], v4 offset0:8 offset1:41
	ds_read2_b32 v[10:11], v4 offset0:74 offset1:107
	ds_read2_b32 v[12:13], v4 offset0:140 offset1:173
	ds_read2_b32 v[14:15], v4 offset0:206 offset1:239
	s_waitcnt lgkmcnt(0)
	v_cvt_pk_bf16_f32 v20, v8, v9
	v_cvt_pk_bf16_f32 v21, v10, v11
	v_cvt_pk_bf16_f32 v22, v12, v13
	v_cvt_pk_bf16_f32 v23, v14, v15
	v_add_u32_e32 v7, 0x8000, v6
	global_store_dwordx4 v7, v[20:23], s[48:49]
	ds_read2_b32 v[8:9], v4 offset0:16 offset1:49
	ds_read2_b32 v[10:11], v4 offset0:82 offset1:115
	ds_read2_b32 v[12:13], v4 offset0:148 offset1:181
	ds_read2_b32 v[14:15], v4 offset0:214 offset1:247
	s_waitcnt lgkmcnt(0)
	v_cvt_pk_bf16_f32 v24, v8, v9
	v_cvt_pk_bf16_f32 v25, v10, v11
	v_cvt_pk_bf16_f32 v26, v12, v13
	v_cvt_pk_bf16_f32 v27, v14, v15
	v_add_u32_e32 v7, 0x10000, v6
	global_store_dwordx4 v7, v[24:27], s[48:49]
	ds_read2_b32 v[8:9], v4 offset0:24 offset1:57
	ds_read2_b32 v[10:11], v4 offset0:90 offset1:123
	ds_read2_b32 v[12:13], v4 offset0:156 offset1:189
	ds_read2_b32 v[14:15], v4 offset0:222 offset1:255
	s_waitcnt lgkmcnt(0)
	v_cvt_pk_bf16_f32 v28, v8, v9
	v_cvt_pk_bf16_f32 v29, v10, v11
	v_cvt_pk_bf16_f32 v30, v12, v13
	v_cvt_pk_bf16_f32 v31, v14, v15
	v_add_u32_e32 v7, 0x18000, v6
	global_store_dwordx4 v7, v[28:31], s[48:49]
	s_add_i32 s3, s0, 1024
	s_mul_i32 s29, s3, 0x1745e
	s_lshr_b32 s29, s29, 25
	s_mul_i32 s35, s29, 0x160
	s_sub_i32 s35, s3, s35
	s_mul_i32 s58, s29, 0x2c0000
	s_lshl_b32 s59, s35, 7
	s_add_u32 s58, s58, s59
	s_add_u32 s46, s10, s58
	s_addc_u32 s47, s11, 0
	global_load_dwordx4 v[16:19], v2, s[46:47] nt
	v_add_u32_e32 v7, 0x58000, v2
	global_load_dwordx4 v[20:23], v7, s[46:47] nt
	v_add_u32_e32 v7, 0xb0000, v2
	global_load_dwordx4 v[24:27], v7, s[46:47] nt
	v_add_u32_e32 v7, 0x108000, v2
	global_load_dwordx4 v[28:31], v7, s[46:47] nt
	v_add_u32_e32 v7, 0x160000, v2
	global_load_dwordx4 v[32:35], v7, s[46:47] nt
	v_add_u32_e32 v7, 0x1b8000, v2
	global_load_dwordx4 v[36:39], v7, s[46:47] nt
	v_add_u32_e32 v7, 0x210000, v2
	global_load_dwordx4 v[40:43], v7, s[46:47] nt
	v_add_u32_e32 v7, 0x268000, v2
	global_load_dwordx4 v[44:47], v7, s[46:47] nt
	s_waitcnt vmcnt(24)
	ds_write_b32 v3, v48
	ds_write_b32 v3, v49 offset:4
	ds_write_b32 v3, v50 offset:8
	ds_write_b32 v3, v51 offset:12
	ds_write_b32 v3, v52 offset:1056
	ds_write_b32 v3, v53 offset:1060
	ds_write_b32 v3, v54 offset:1064
	ds_write_b32 v3, v55 offset:1068
	ds_write_b32 v3, v56 offset:2112
	ds_write_b32 v3, v57 offset:2116
	ds_write_b32 v3, v58 offset:2120
	ds_write_b32 v3, v59 offset:2124
	ds_write_b32 v3, v60 offset:3168
	ds_write_b32 v3, v61 offset:3172
	ds_write_b32 v3, v62 offset:3176
	ds_write_b32 v3, v63 offset:3180
	ds_write_b32 v3, v64 offset:4224
	ds_write_b32 v3, v65 offset:4228
	ds_write_b32 v3, v66 offset:4232
	ds_write_b32 v3, v67 offset:4236
	ds_write_b32 v3, v68 offset:5280
	ds_write_b32 v3, v69 offset:5284
	ds_write_b32 v3, v70 offset:5288
	ds_write_b32 v3, v71 offset:5292
	ds_write_b32 v3, v72 offset:6336
	ds_write_b32 v3, v73 offset:6340
	ds_write_b32 v3, v74 offset:6344
	ds_write_b32 v3, v75 offset:6348
	ds_write_b32 v3, v76 offset:7392
	ds_write_b32 v3, v77 offset:7396
	ds_write_b32 v3, v78 offset:7400
	ds_write_b32 v3, v79 offset:7404
	s_waitcnt lgkmcnt(0)
	s_add_i32 s3, s0, 1024
	s_lshr_b32 s29, s3, 6
	s_and_b32 s35, s3, 63
	s_lshl_b32 s58, s35, 17
	s_lshl_b32 s59, s29, 7
	s_add_u32 s58, s58, s59
	s_add_u32 s48, s30, s58
	s_addc_u32 s49, s31, 0
	ds_read2_b32 v[8:9], v4 offset0:0 offset1:33
	ds_read2_b32 v[10:11], v4 offset0:66 offset1:99
	ds_read2_b32 v[12:13], v4 offset0:132 offset1:165
	ds_read2_b32 v[14:15], v4 offset0:198 offset1:231
	s_waitcnt lgkmcnt(0)
	v_cvt_pk_bf16_f32 v48, v8, v9
	v_cvt_pk_bf16_f32 v49, v10, v11
	v_cvt_pk_bf16_f32 v50, v12, v13
	v_cvt_pk_bf16_f32 v51, v14, v15
	global_store_dwordx4 v6, v[48:51], s[48:49]
	ds_read2_b32 v[8:9], v4 offset0:8 offset1:41
	ds_read2_b32 v[10:11], v4 offset0:74 offset1:107
	ds_read2_b32 v[12:13], v4 offset0:140 offset1:173
	ds_read2_b32 v[14:15], v4 offset0:206 offset1:239
	s_waitcnt lgkmcnt(0)
	v_cvt_pk_bf16_f32 v52, v8, v9
	v_cvt_pk_bf16_f32 v53, v10, v11
	v_cvt_pk_bf16_f32 v54, v12, v13
	v_cvt_pk_bf16_f32 v55, v14, v15
	v_add_u32_e32 v7, 0x8000, v6
	global_store_dwordx4 v7, v[52:55], s[48:49]
	ds_read2_b32 v[8:9], v4 offset0:16 offset1:49
	ds_read2_b32 v[10:11], v4 offset0:82 offset1:115
	ds_read2_b32 v[12:13], v4 offset0:148 offset1:181
	ds_read2_b32 v[14:15], v4 offset0:214 offset1:247
	s_waitcnt lgkmcnt(0)
	v_cvt_pk_bf16_f32 v56, v8, v9
	v_cvt_pk_bf16_f32 v57, v10, v11
	v_cvt_pk_bf16_f32 v58, v12, v13
	v_cvt_pk_bf16_f32 v59, v14, v15
	v_add_u32_e32 v7, 0x10000, v6
	global_store_dwordx4 v7, v[56:59], s[48:49]
	ds_read2_b32 v[8:9], v4 offset0:24 offset1:57
	ds_read2_b32 v[10:11], v4 offset0:90 offset1:123
	ds_read2_b32 v[12:13], v4 offset0:156 offset1:189
	ds_read2_b32 v[14:15], v4 offset0:222 offset1:255
	s_waitcnt lgkmcnt(0)
	v_cvt_pk_bf16_f32 v60, v8, v9
	v_cvt_pk_bf16_f32 v61, v10, v11
	v_cvt_pk_bf16_f32 v62, v12, v13
	v_cvt_pk_bf16_f32 v63, v14, v15
	v_add_u32_e32 v7, 0x18000, v6
	global_store_dwordx4 v7, v[60:63], s[48:49]
	s_add_i32 s3, s0, 2048
	s_mul_i32 s29, s3, 0x1745e
	s_lshr_b32 s29, s29, 25
	s_mul_i32 s35, s29, 0x160
	s_sub_i32 s35, s3, s35
	s_mul_i32 s58, s29, 0x2c0000
	s_lshl_b32 s59, s35, 7
	s_add_u32 s58, s58, s59
	s_add_u32 s46, s10, s58
	s_addc_u32 s47, s11, 0
	global_load_dwordx4 v[48:51], v2, s[46:47] nt
	v_add_u32_e32 v7, 0x58000, v2
	global_load_dwordx4 v[52:55], v7, s[46:47] nt
	v_add_u32_e32 v7, 0xb0000, v2
	global_load_dwordx4 v[56:59], v7, s[46:47] nt
	v_add_u32_e32 v7, 0x108000, v2
	global_load_dwordx4 v[60:63], v7, s[46:47] nt
	v_add_u32_e32 v7, 0x160000, v2
	global_load_dwordx4 v[64:67], v7, s[46:47] nt
	v_add_u32_e32 v7, 0x1b8000, v2
	global_load_dwordx4 v[68:71], v7, s[46:47] nt
	v_add_u32_e32 v7, 0x210000, v2
	global_load_dwordx4 v[72:75], v7, s[46:47] nt
	v_add_u32_e32 v7, 0x268000, v2
	global_load_dwordx4 v[76:79], v7, s[46:47] nt
	s_waitcnt vmcnt(24)
	ds_write_b32 v3, v80
	ds_write_b32 v3, v81 offset:4
	ds_write_b32 v3, v82 offset:8
	ds_write_b32 v3, v83 offset:12
	ds_write_b32 v3, v84 offset:1056
	ds_write_b32 v3, v85 offset:1060
	ds_write_b32 v3, v86 offset:1064
	ds_write_b32 v3, v87 offset:1068
	ds_write_b32 v3, v88 offset:2112
	ds_write_b32 v3, v89 offset:2116
	ds_write_b32 v3, v90 offset:2120
	ds_write_b32 v3, v91 offset:2124
	ds_write_b32 v3, v92 offset:3168
	ds_write_b32 v3, v93 offset:3172
	ds_write_b32 v3, v94 offset:3176
	ds_write_b32 v3, v95 offset:3180
	ds_write_b32 v3, v96 offset:4224
	ds_write_b32 v3, v97 offset:4228
	ds_write_b32 v3, v98 offset:4232
	ds_write_b32 v3, v99 offset:4236
	ds_write_b32 v3, v100 offset:5280
	ds_write_b32 v3, v101 offset:5284
	ds_write_b32 v3, v102 offset:5288
	ds_write_b32 v3, v103 offset:5292
	ds_write_b32 v3, v104 offset:6336
	ds_write_b32 v3, v105 offset:6340
	ds_write_b32 v3, v106 offset:6344
	ds_write_b32 v3, v107 offset:6348
	ds_write_b32 v3, v108 offset:7392
	ds_write_b32 v3, v109 offset:7396
	ds_write_b32 v3, v110 offset:7400
	ds_write_b32 v3, v111 offset:7404
	s_waitcnt lgkmcnt(0)
	s_mov_b32 s3, s0
	s_mul_i32 s29, s3, 0x1745e
	s_lshr_b32 s29, s29, 25
	s_mul_i32 s35, s29, 0x160
	s_sub_i32 s35, s3, s35
	s_lshl_b32 s58, s35, 17
	s_lshl_b32 s59, s29, 7
	s_add_u32 s58, s58, s59
	s_add_u32 s48, s42, s58
	s_addc_u32 s49, s43, 0
	ds_read2_b32 v[8:9], v4 offset0:0 offset1:33
	ds_read2_b32 v[10:11], v4 offset0:66 offset1:99
	ds_read2_b32 v[12:13], v4 offset0:132 offset1:165
	ds_read2_b32 v[14:15], v4 offset0:198 offset1:231
	s_waitcnt lgkmcnt(0)
	v_cvt_pk_bf16_f32 v80, v8, v9
	v_cvt_pk_bf16_f32 v81, v10, v11
	v_cvt_pk_bf16_f32 v82, v12, v13
	v_cvt_pk_bf16_f32 v83, v14, v15
	global_store_dwordx4 v6, v[80:83], s[48:49]
	ds_read2_b32 v[8:9], v4 offset0:8 offset1:41
	ds_read2_b32 v[10:11], v4 offset0:74 offset1:107
	ds_read2_b32 v[12:13], v4 offset0:140 offset1:173
	ds_read2_b32 v[14:15], v4 offset0:206 offset1:239
	s_waitcnt lgkmcnt(0)
	v_cvt_pk_bf16_f32 v84, v8, v9
	v_cvt_pk_bf16_f32 v85, v10, v11
	v_cvt_pk_bf16_f32 v86, v12, v13
	v_cvt_pk_bf16_f32 v87, v14, v15
	v_add_u32_e32 v7, 0x8000, v6
	global_store_dwordx4 v7, v[84:87], s[48:49]
	ds_read2_b32 v[8:9], v4 offset0:16 offset1:49
	ds_read2_b32 v[10:11], v4 offset0:82 offset1:115
	ds_read2_b32 v[12:13], v4 offset0:148 offset1:181
	ds_read2_b32 v[14:15], v4 offset0:214 offset1:247
	s_waitcnt lgkmcnt(0)
	v_cvt_pk_bf16_f32 v88, v8, v9
	v_cvt_pk_bf16_f32 v89, v10, v11
	v_cvt_pk_bf16_f32 v90, v12, v13
	v_cvt_pk_bf16_f32 v91, v14, v15
	v_add_u32_e32 v7, 0x10000, v6
	global_store_dwordx4 v7, v[88:91], s[48:49]
	ds_read2_b32 v[8:9], v4 offset0:24 offset1:57
	ds_read2_b32 v[10:11], v4 offset0:90 offset1:123
	ds_read2_b32 v[12:13], v4 offset0:156 offset1:189
	ds_read2_b32 v[14:15], v4 offset0:222 offset1:255
	s_waitcnt lgkmcnt(0)
	v_cvt_pk_bf16_f32 v92, v8, v9
	v_cvt_pk_bf16_f32 v93, v10, v11
	v_cvt_pk_bf16_f32 v94, v12, v13
	v_cvt_pk_bf16_f32 v95, v14, v15
	v_add_u32_e32 v7, 0x18000, v6
	global_store_dwordx4 v7, v[92:95], s[48:49]
	s_add_i32 s3, s0, 3072
	s_mul_i32 s29, s3, 0x1745e
	s_lshr_b32 s29, s29, 25
	s_mul_i32 s35, s29, 0x160
	s_sub_i32 s35, s3, s35
	s_mul_i32 s58, s29, 0x2c0000
	s_lshl_b32 s59, s35, 7
	s_add_u32 s58, s58, s59
	s_add_u32 s46, s10, s58
	s_addc_u32 s47, s11, 0
	global_load_dwordx4 v[80:83], v2, s[46:47] nt
	v_add_u32_e32 v7, 0x58000, v2
	global_load_dwordx4 v[84:87], v7, s[46:47] nt
	v_add_u32_e32 v7, 0xb0000, v2
	global_load_dwordx4 v[88:91], v7, s[46:47] nt
	v_add_u32_e32 v7, 0x108000, v2
	global_load_dwordx4 v[92:95], v7, s[46:47] nt
	v_add_u32_e32 v7, 0x160000, v2
	global_load_dwordx4 v[96:99], v7, s[46:47] nt
	v_add_u32_e32 v7, 0x1b8000, v2
	global_load_dwordx4 v[100:103], v7, s[46:47] nt
	v_add_u32_e32 v7, 0x210000, v2
	global_load_dwordx4 v[104:107], v7, s[46:47] nt
	v_add_u32_e32 v7, 0x268000, v2
	global_load_dwordx4 v[108:111], v7, s[46:47] nt
	s_waitcnt vmcnt(24)
	ds_write_b32 v3, v16
	ds_write_b32 v3, v17 offset:4
	ds_write_b32 v3, v18 offset:8
	ds_write_b32 v3, v19 offset:12
	ds_write_b32 v3, v20 offset:1056
	ds_write_b32 v3, v21 offset:1060
	ds_write_b32 v3, v22 offset:1064
	ds_write_b32 v3, v23 offset:1068
	ds_write_b32 v3, v24 offset:2112
	ds_write_b32 v3, v25 offset:2116
	ds_write_b32 v3, v26 offset:2120
	ds_write_b32 v3, v27 offset:2124
	ds_write_b32 v3, v28 offset:3168
	ds_write_b32 v3, v29 offset:3172
	ds_write_b32 v3, v30 offset:3176
	ds_write_b32 v3, v31 offset:3180
	ds_write_b32 v3, v32 offset:4224
	ds_write_b32 v3, v33 offset:4228
	ds_write_b32 v3, v34 offset:4232
	ds_write_b32 v3, v35 offset:4236
	ds_write_b32 v3, v36 offset:5280
	ds_write_b32 v3, v37 offset:5284
	ds_write_b32 v3, v38 offset:5288
	ds_write_b32 v3, v39 offset:5292
	ds_write_b32 v3, v40 offset:6336
	ds_write_b32 v3, v41 offset:6340
	ds_write_b32 v3, v42 offset:6344
	ds_write_b32 v3, v43 offset:6348
	ds_write_b32 v3, v44 offset:7392
	ds_write_b32 v3, v45 offset:7396
	ds_write_b32 v3, v46 offset:7400
	ds_write_b32 v3, v47 offset:7404
	s_waitcnt lgkmcnt(0)
	s_add_i32 s3, s0, 1024
	s_mul_i32 s29, s3, 0x1745e
	s_lshr_b32 s29, s29, 25
	s_mul_i32 s35, s29, 0x160
	s_sub_i32 s35, s3, s35
	s_lshl_b32 s58, s35, 17
	s_lshl_b32 s59, s29, 7
	s_add_u32 s58, s58, s59
	s_add_u32 s48, s42, s58
	s_addc_u32 s49, s43, 0
	ds_read2_b32 v[8:9], v4 offset0:0 offset1:33
	ds_read2_b32 v[10:11], v4 offset0:66 offset1:99
	ds_read2_b32 v[12:13], v4 offset0:132 offset1:165
	ds_read2_b32 v[14:15], v4 offset0:198 offset1:231
	s_waitcnt lgkmcnt(0)
	v_cvt_pk_bf16_f32 v16, v8, v9
	v_cvt_pk_bf16_f32 v17, v10, v11
	v_cvt_pk_bf16_f32 v18, v12, v13
	v_cvt_pk_bf16_f32 v19, v14, v15
	global_store_dwordx4 v6, v[16:19], s[48:49]
	ds_read2_b32 v[8:9], v4 offset0:8 offset1:41
	ds_read2_b32 v[10:11], v4 offset0:74 offset1:107
	ds_read2_b32 v[12:13], v4 offset0:140 offset1:173
	ds_read2_b32 v[14:15], v4 offset0:206 offset1:239
	s_waitcnt lgkmcnt(0)
	v_cvt_pk_bf16_f32 v20, v8, v9
	v_cvt_pk_bf16_f32 v21, v10, v11
	v_cvt_pk_bf16_f32 v22, v12, v13
	v_cvt_pk_bf16_f32 v23, v14, v15
	v_add_u32_e32 v7, 0x8000, v6
	global_store_dwordx4 v7, v[20:23], s[48:49]
	ds_read2_b32 v[8:9], v4 offset0:16 offset1:49
	ds_read2_b32 v[10:11], v4 offset0:82 offset1:115
	ds_read2_b32 v[12:13], v4 offset0:148 offset1:181
	ds_read2_b32 v[14:15], v4 offset0:214 offset1:247
	s_waitcnt lgkmcnt(0)
	v_cvt_pk_bf16_f32 v24, v8, v9
	v_cvt_pk_bf16_f32 v25, v10, v11
	v_cvt_pk_bf16_f32 v26, v12, v13
	v_cvt_pk_bf16_f32 v27, v14, v15
	v_add_u32_e32 v7, 0x10000, v6
	global_store_dwordx4 v7, v[24:27], s[48:49]
	ds_read2_b32 v[8:9], v4 offset0:24 offset1:57
	ds_read2_b32 v[10:11], v4 offset0:90 offset1:123
	ds_read2_b32 v[12:13], v4 offset0:156 offset1:189
	ds_read2_b32 v[14:15], v4 offset0:222 offset1:255
	s_waitcnt lgkmcnt(0)
	v_cvt_pk_bf16_f32 v28, v8, v9
	v_cvt_pk_bf16_f32 v29, v10, v11
	v_cvt_pk_bf16_f32 v30, v12, v13
	v_cvt_pk_bf16_f32 v31, v14, v15
	v_add_u32_e32 v7, 0x18000, v6
	global_store_dwordx4 v7, v[28:31], s[48:49]
	s_add_i32 s3, s0, 4096
	s_mul_i32 s29, s3, 0x1745e
	s_lshr_b32 s29, s29, 25
	s_mul_i32 s35, s29, 0x160
	s_sub_i32 s35, s3, s35
	s_mul_i32 s58, s29, 0x2c0000
	s_lshl_b32 s59, s35, 7
	s_add_u32 s58, s58, s59
	s_add_u32 s46, s10, s58
	s_addc_u32 s47, s11, 0
	global_load_dwordx4 v[16:19], v2, s[46:47] nt
	v_add_u32_e32 v7, 0x58000, v2
	global_load_dwordx4 v[20:23], v7, s[46:47] nt
	v_add_u32_e32 v7, 0xb0000, v2
	global_load_dwordx4 v[24:27], v7, s[46:47] nt
	v_add_u32_e32 v7, 0x108000, v2
	global_load_dwordx4 v[28:31], v7, s[46:47] nt
	v_add_u32_e32 v7, 0x160000, v2
	global_load_dwordx4 v[32:35], v7, s[46:47] nt
	v_add_u32_e32 v7, 0x1b8000, v2
	global_load_dwordx4 v[36:39], v7, s[46:47] nt
	v_add_u32_e32 v7, 0x210000, v2
	global_load_dwordx4 v[40:43], v7, s[46:47] nt
	v_add_u32_e32 v7, 0x268000, v2
	global_load_dwordx4 v[44:47], v7, s[46:47] nt
	s_waitcnt vmcnt(24)
	ds_write_b32 v3, v48
	ds_write_b32 v3, v49 offset:4
	ds_write_b32 v3, v50 offset:8
	ds_write_b32 v3, v51 offset:12
	ds_write_b32 v3, v52 offset:1056
	ds_write_b32 v3, v53 offset:1060
	ds_write_b32 v3, v54 offset:1064
	ds_write_b32 v3, v55 offset:1068
	ds_write_b32 v3, v56 offset:2112
	ds_write_b32 v3, v57 offset:2116
	ds_write_b32 v3, v58 offset:2120
	ds_write_b32 v3, v59 offset:2124
	ds_write_b32 v3, v60 offset:3168
	ds_write_b32 v3, v61 offset:3172
	ds_write_b32 v3, v62 offset:3176
	ds_write_b32 v3, v63 offset:3180
	ds_write_b32 v3, v64 offset:4224
	ds_write_b32 v3, v65 offset:4228
	ds_write_b32 v3, v66 offset:4232
	ds_write_b32 v3, v67 offset:4236
	ds_write_b32 v3, v68 offset:5280
	ds_write_b32 v3, v69 offset:5284
	ds_write_b32 v3, v70 offset:5288
	ds_write_b32 v3, v71 offset:5292
	ds_write_b32 v3, v72 offset:6336
	ds_write_b32 v3, v73 offset:6340
	ds_write_b32 v3, v74 offset:6344
	ds_write_b32 v3, v75 offset:6348
	ds_write_b32 v3, v76 offset:7392
	ds_write_b32 v3, v77 offset:7396
	ds_write_b32 v3, v78 offset:7400
	ds_write_b32 v3, v79 offset:7404
	s_waitcnt lgkmcnt(0)
	s_add_i32 s3, s0, 2048
	s_mul_i32 s29, s3, 0x1745e
	s_lshr_b32 s29, s29, 25
	s_mul_i32 s35, s29, 0x160
	s_sub_i32 s35, s3, s35
	s_lshl_b32 s58, s35, 17
	s_lshl_b32 s59, s29, 7
	s_add_u32 s58, s58, s59
	s_add_u32 s48, s42, s58
	s_addc_u32 s49, s43, 0
	ds_read2_b32 v[8:9], v4 offset0:0 offset1:33
	ds_read2_b32 v[10:11], v4 offset0:66 offset1:99
	ds_read2_b32 v[12:13], v4 offset0:132 offset1:165
	ds_read2_b32 v[14:15], v4 offset0:198 offset1:231
	s_waitcnt lgkmcnt(0)
	v_cvt_pk_bf16_f32 v48, v8, v9
	v_cvt_pk_bf16_f32 v49, v10, v11
	v_cvt_pk_bf16_f32 v50, v12, v13
	v_cvt_pk_bf16_f32 v51, v14, v15
	global_store_dwordx4 v6, v[48:51], s[48:49]
	ds_read2_b32 v[8:9], v4 offset0:8 offset1:41
	ds_read2_b32 v[10:11], v4 offset0:74 offset1:107
	ds_read2_b32 v[12:13], v4 offset0:140 offset1:173
	ds_read2_b32 v[14:15], v4 offset0:206 offset1:239
	s_waitcnt lgkmcnt(0)
	v_cvt_pk_bf16_f32 v52, v8, v9
	v_cvt_pk_bf16_f32 v53, v10, v11
	v_cvt_pk_bf16_f32 v54, v12, v13
	v_cvt_pk_bf16_f32 v55, v14, v15
	v_add_u32_e32 v7, 0x8000, v6
	global_store_dwordx4 v7, v[52:55], s[48:49]
	ds_read2_b32 v[8:9], v4 offset0:16 offset1:49
	ds_read2_b32 v[10:11], v4 offset0:82 offset1:115
	ds_read2_b32 v[12:13], v4 offset0:148 offset1:181
	ds_read2_b32 v[14:15], v4 offset0:214 offset1:247
	s_waitcnt lgkmcnt(0)
	v_cvt_pk_bf16_f32 v56, v8, v9
	v_cvt_pk_bf16_f32 v57, v10, v11
	v_cvt_pk_bf16_f32 v58, v12, v13
	v_cvt_pk_bf16_f32 v59, v14, v15
	v_add_u32_e32 v7, 0x10000, v6
	global_store_dwordx4 v7, v[56:59], s[48:49]
	ds_read2_b32 v[8:9], v4 offset0:24 offset1:57
	ds_read2_b32 v[10:11], v4 offset0:90 offset1:123
	ds_read2_b32 v[12:13], v4 offset0:156 offset1:189
	ds_read2_b32 v[14:15], v4 offset0:222 offset1:255
	s_waitcnt lgkmcnt(0)
	v_cvt_pk_bf16_f32 v60, v8, v9
	v_cvt_pk_bf16_f32 v61, v10, v11
	v_cvt_pk_bf16_f32 v62, v12, v13
	v_cvt_pk_bf16_f32 v63, v14, v15
	v_add_u32_e32 v7, 0x18000, v6
	global_store_dwordx4 v7, v[60:63], s[48:49]
	s_add_i32 s3, s0, 5120
	s_mul_i32 s29, s3, 0x1745e
	s_lshr_b32 s29, s29, 25
	s_mul_i32 s35, s29, 0x160
	s_sub_i32 s35, s3, s35
	s_mul_i32 s58, s29, 0x2c0000
	s_lshl_b32 s59, s35, 7
	s_add_u32 s58, s58, s59
	s_add_u32 s46, s10, s58
	s_addc_u32 s47, s11, 0
	global_load_dwordx4 v[48:51], v2, s[46:47] nt
	v_add_u32_e32 v7, 0x58000, v2
	global_load_dwordx4 v[52:55], v7, s[46:47] nt
	v_add_u32_e32 v7, 0xb0000, v2
	global_load_dwordx4 v[56:59], v7, s[46:47] nt
	v_add_u32_e32 v7, 0x108000, v2
	global_load_dwordx4 v[60:63], v7, s[46:47] nt
	v_add_u32_e32 v7, 0x160000, v2
	global_load_dwordx4 v[64:67], v7, s[46:47] nt
	v_add_u32_e32 v7, 0x1b8000, v2
	global_load_dwordx4 v[68:71], v7, s[46:47] nt
	v_add_u32_e32 v7, 0x210000, v2
	global_load_dwordx4 v[72:75], v7, s[46:47] nt
	v_add_u32_e32 v7, 0x268000, v2
	global_load_dwordx4 v[76:79], v7, s[46:47] nt
	s_waitcnt vmcnt(24)
	ds_write_b32 v3, v80
	ds_write_b32 v3, v81 offset:4
	ds_write_b32 v3, v82 offset:8
	ds_write_b32 v3, v83 offset:12
	ds_write_b32 v3, v84 offset:1056
	ds_write_b32 v3, v85 offset:1060
	ds_write_b32 v3, v86 offset:1064
	ds_write_b32 v3, v87 offset:1068
	ds_write_b32 v3, v88 offset:2112
	ds_write_b32 v3, v89 offset:2116
	ds_write_b32 v3, v90 offset:2120
	ds_write_b32 v3, v91 offset:2124
	ds_write_b32 v3, v92 offset:3168
	ds_write_b32 v3, v93 offset:3172
	ds_write_b32 v3, v94 offset:3176
	ds_write_b32 v3, v95 offset:3180
	ds_write_b32 v3, v96 offset:4224
	ds_write_b32 v3, v97 offset:4228
	ds_write_b32 v3, v98 offset:4232
	ds_write_b32 v3, v99 offset:4236
	ds_write_b32 v3, v100 offset:5280
	ds_write_b32 v3, v101 offset:5284
	ds_write_b32 v3, v102 offset:5288
	ds_write_b32 v3, v103 offset:5292
	ds_write_b32 v3, v104 offset:6336
	ds_write_b32 v3, v105 offset:6340
	ds_write_b32 v3, v106 offset:6344
	ds_write_b32 v3, v107 offset:6348
	ds_write_b32 v3, v108 offset:7392
	ds_write_b32 v3, v109 offset:7396
	ds_write_b32 v3, v110 offset:7400
	ds_write_b32 v3, v111 offset:7404
	s_waitcnt lgkmcnt(0)
	s_add_i32 s3, s0, 3072
	s_mul_i32 s29, s3, 0x1745e
	s_lshr_b32 s29, s29, 25
	s_mul_i32 s35, s29, 0x160
	s_sub_i32 s35, s3, s35
	s_lshl_b32 s58, s35, 17
	s_lshl_b32 s59, s29, 7
	s_add_u32 s58, s58, s59
	s_add_u32 s48, s42, s58
	s_addc_u32 s49, s43, 0
	ds_read2_b32 v[8:9], v4 offset0:0 offset1:33
	ds_read2_b32 v[10:11], v4 offset0:66 offset1:99
	ds_read2_b32 v[12:13], v4 offset0:132 offset1:165
	ds_read2_b32 v[14:15], v4 offset0:198 offset1:231
	s_waitcnt lgkmcnt(0)
	v_cvt_pk_bf16_f32 v80, v8, v9
	v_cvt_pk_bf16_f32 v81, v10, v11
	v_cvt_pk_bf16_f32 v82, v12, v13
	v_cvt_pk_bf16_f32 v83, v14, v15
	global_store_dwordx4 v6, v[80:83], s[48:49]
	ds_read2_b32 v[8:9], v4 offset0:8 offset1:41
	ds_read2_b32 v[10:11], v4 offset0:74 offset1:107
	ds_read2_b32 v[12:13], v4 offset0:140 offset1:173
	ds_read2_b32 v[14:15], v4 offset0:206 offset1:239
	s_waitcnt lgkmcnt(0)
	v_cvt_pk_bf16_f32 v84, v8, v9
	v_cvt_pk_bf16_f32 v85, v10, v11
	v_cvt_pk_bf16_f32 v86, v12, v13
	v_cvt_pk_bf16_f32 v87, v14, v15
	v_add_u32_e32 v7, 0x8000, v6
	global_store_dwordx4 v7, v[84:87], s[48:49]
	ds_read2_b32 v[8:9], v4 offset0:16 offset1:49
	ds_read2_b32 v[10:11], v4 offset0:82 offset1:115
	ds_read2_b32 v[12:13], v4 offset0:148 offset1:181
	ds_read2_b32 v[14:15], v4 offset0:214 offset1:247
	s_waitcnt lgkmcnt(0)
	v_cvt_pk_bf16_f32 v88, v8, v9
	v_cvt_pk_bf16_f32 v89, v10, v11
	v_cvt_pk_bf16_f32 v90, v12, v13
	v_cvt_pk_bf16_f32 v91, v14, v15
	v_add_u32_e32 v7, 0x10000, v6
	global_store_dwordx4 v7, v[88:91], s[48:49]
	ds_read2_b32 v[8:9], v4 offset0:24 offset1:57
	ds_read2_b32 v[10:11], v4 offset0:90 offset1:123
	ds_read2_b32 v[12:13], v4 offset0:156 offset1:189
	ds_read2_b32 v[14:15], v4 offset0:222 offset1:255
	s_waitcnt lgkmcnt(0)
	v_cvt_pk_bf16_f32 v92, v8, v9
	v_cvt_pk_bf16_f32 v93, v10, v11
	v_cvt_pk_bf16_f32 v94, v12, v13
	v_cvt_pk_bf16_f32 v95, v14, v15
	v_add_u32_e32 v7, 0x18000, v6
	global_store_dwordx4 v7, v[92:95], s[48:49]
	s_add_i32 s3, s0, 6144
	s_mul_i32 s29, s3, 0x1745e
	s_lshr_b32 s29, s29, 25
	s_mul_i32 s35, s29, 0x160
	s_sub_i32 s35, s3, s35
	s_mul_i32 s58, s29, 0x2c0000
	s_lshl_b32 s59, s35, 7
	s_add_u32 s58, s58, s59
	s_add_u32 s46, s10, s58
	s_addc_u32 s47, s11, 0
	global_load_dwordx4 v[80:83], v2, s[46:47] nt
	v_add_u32_e32 v7, 0x58000, v2
	global_load_dwordx4 v[84:87], v7, s[46:47] nt
	v_add_u32_e32 v7, 0xb0000, v2
	global_load_dwordx4 v[88:91], v7, s[46:47] nt
	v_add_u32_e32 v7, 0x108000, v2
	global_load_dwordx4 v[92:95], v7, s[46:47] nt
	v_add_u32_e32 v7, 0x160000, v2
	global_load_dwordx4 v[96:99], v7, s[46:47] nt
	v_add_u32_e32 v7, 0x1b8000, v2
	global_load_dwordx4 v[100:103], v7, s[46:47] nt
	v_add_u32_e32 v7, 0x210000, v2
	global_load_dwordx4 v[104:107], v7, s[46:47] nt
	v_add_u32_e32 v7, 0x268000, v2
	global_load_dwordx4 v[108:111], v7, s[46:47] nt
	s_waitcnt vmcnt(24)
	ds_write_b32 v3, v16
	ds_write_b32 v3, v17 offset:4
	ds_write_b32 v3, v18 offset:8
	ds_write_b32 v3, v19 offset:12
	ds_write_b32 v3, v20 offset:1056
	ds_write_b32 v3, v21 offset:1060
	ds_write_b32 v3, v22 offset:1064
	ds_write_b32 v3, v23 offset:1068
	ds_write_b32 v3, v24 offset:2112
	ds_write_b32 v3, v25 offset:2116
	ds_write_b32 v3, v26 offset:2120
	ds_write_b32 v3, v27 offset:2124
	ds_write_b32 v3, v28 offset:3168
	ds_write_b32 v3, v29 offset:3172
	ds_write_b32 v3, v30 offset:3176
	ds_write_b32 v3, v31 offset:3180
	ds_write_b32 v3, v32 offset:4224
	ds_write_b32 v3, v33 offset:4228
	ds_write_b32 v3, v34 offset:4232
	ds_write_b32 v3, v35 offset:4236
	ds_write_b32 v3, v36 offset:5280
	ds_write_b32 v3, v37 offset:5284
	ds_write_b32 v3, v38 offset:5288
	ds_write_b32 v3, v39 offset:5292
	ds_write_b32 v3, v40 offset:6336
	ds_write_b32 v3, v41 offset:6340
	ds_write_b32 v3, v42 offset:6344
	ds_write_b32 v3, v43 offset:6348
	ds_write_b32 v3, v44 offset:7392
	ds_write_b32 v3, v45 offset:7396
	ds_write_b32 v3, v46 offset:7400
	ds_write_b32 v3, v47 offset:7404
	s_waitcnt lgkmcnt(0)
	s_add_i32 s3, s0, 4096
	s_mul_i32 s29, s3, 0x1745e
	s_lshr_b32 s29, s29, 25
	s_mul_i32 s35, s29, 0x160
	s_sub_i32 s35, s3, s35
	s_lshl_b32 s58, s35, 17
	s_lshl_b32 s59, s29, 7
	s_add_u32 s58, s58, s59
	s_add_u32 s48, s42, s58
	s_addc_u32 s49, s43, 0
	ds_read2_b32 v[8:9], v4 offset0:0 offset1:33
	ds_read2_b32 v[10:11], v4 offset0:66 offset1:99
	ds_read2_b32 v[12:13], v4 offset0:132 offset1:165
	ds_read2_b32 v[14:15], v4 offset0:198 offset1:231
	s_waitcnt lgkmcnt(0)
	v_cvt_pk_bf16_f32 v16, v8, v9
	v_cvt_pk_bf16_f32 v17, v10, v11
	v_cvt_pk_bf16_f32 v18, v12, v13
	v_cvt_pk_bf16_f32 v19, v14, v15
	global_store_dwordx4 v6, v[16:19], s[48:49]
	ds_read2_b32 v[8:9], v4 offset0:8 offset1:41
	ds_read2_b32 v[10:11], v4 offset0:74 offset1:107
	ds_read2_b32 v[12:13], v4 offset0:140 offset1:173
	ds_read2_b32 v[14:15], v4 offset0:206 offset1:239
	s_waitcnt lgkmcnt(0)
	v_cvt_pk_bf16_f32 v20, v8, v9
	v_cvt_pk_bf16_f32 v21, v10, v11
	v_cvt_pk_bf16_f32 v22, v12, v13
	v_cvt_pk_bf16_f32 v23, v14, v15
	v_add_u32_e32 v7, 0x8000, v6
	global_store_dwordx4 v7, v[20:23], s[48:49]
	ds_read2_b32 v[8:9], v4 offset0:16 offset1:49
	ds_read2_b32 v[10:11], v4 offset0:82 offset1:115
	ds_read2_b32 v[12:13], v4 offset0:148 offset1:181
	ds_read2_b32 v[14:15], v4 offset0:214 offset1:247
	s_waitcnt lgkmcnt(0)
	v_cvt_pk_bf16_f32 v24, v8, v9
	v_cvt_pk_bf16_f32 v25, v10, v11
	v_cvt_pk_bf16_f32 v26, v12, v13
	v_cvt_pk_bf16_f32 v27, v14, v15
	v_add_u32_e32 v7, 0x10000, v6
	global_store_dwordx4 v7, v[24:27], s[48:49]
	ds_read2_b32 v[8:9], v4 offset0:24 offset1:57
	ds_read2_b32 v[10:11], v4 offset0:90 offset1:123
	ds_read2_b32 v[12:13], v4 offset0:156 offset1:189
	ds_read2_b32 v[14:15], v4 offset0:222 offset1:255
	s_waitcnt lgkmcnt(0)
	v_cvt_pk_bf16_f32 v28, v8, v9
	v_cvt_pk_bf16_f32 v29, v10, v11
	v_cvt_pk_bf16_f32 v30, v12, v13
	v_cvt_pk_bf16_f32 v31, v14, v15
	v_add_u32_e32 v7, 0x18000, v6
	global_store_dwordx4 v7, v[28:31], s[48:49]
	s_add_i32 s3, s0, 7168
	s_mul_i32 s29, s3, 0x1745e
	s_lshr_b32 s29, s29, 25
	s_mul_i32 s35, s29, 0x160
	s_sub_i32 s35, s3, s35
	s_mul_i32 s58, s29, 0x2c0000
	s_lshl_b32 s59, s35, 7
	s_add_u32 s58, s58, s59
	s_add_u32 s46, s10, s58
	s_addc_u32 s47, s11, 0
	global_load_dwordx4 v[16:19], v2, s[46:47] nt
	v_add_u32_e32 v7, 0x58000, v2
	global_load_dwordx4 v[20:23], v7, s[46:47] nt
	v_add_u32_e32 v7, 0xb0000, v2
	global_load_dwordx4 v[24:27], v7, s[46:47] nt
	v_add_u32_e32 v7, 0x108000, v2
	global_load_dwordx4 v[28:31], v7, s[46:47] nt
	v_add_u32_e32 v7, 0x160000, v2
	global_load_dwordx4 v[32:35], v7, s[46:47] nt
	v_add_u32_e32 v7, 0x1b8000, v2
	global_load_dwordx4 v[36:39], v7, s[46:47] nt
	v_add_u32_e32 v7, 0x210000, v2
	global_load_dwordx4 v[40:43], v7, s[46:47] nt
	v_add_u32_e32 v7, 0x268000, v2
	global_load_dwordx4 v[44:47], v7, s[46:47] nt
	s_waitcnt vmcnt(24)
	ds_write_b32 v3, v48
	ds_write_b32 v3, v49 offset:4
	ds_write_b32 v3, v50 offset:8
	ds_write_b32 v3, v51 offset:12
	ds_write_b32 v3, v52 offset:1056
	ds_write_b32 v3, v53 offset:1060
	ds_write_b32 v3, v54 offset:1064
	ds_write_b32 v3, v55 offset:1068
	ds_write_b32 v3, v56 offset:2112
	ds_write_b32 v3, v57 offset:2116
	ds_write_b32 v3, v58 offset:2120
	ds_write_b32 v3, v59 offset:2124
	ds_write_b32 v3, v60 offset:3168
	ds_write_b32 v3, v61 offset:3172
	ds_write_b32 v3, v62 offset:3176
	ds_write_b32 v3, v63 offset:3180
	ds_write_b32 v3, v64 offset:4224
	ds_write_b32 v3, v65 offset:4228
	ds_write_b32 v3, v66 offset:4232
	ds_write_b32 v3, v67 offset:4236
	ds_write_b32 v3, v68 offset:5280
	ds_write_b32 v3, v69 offset:5284
	ds_write_b32 v3, v70 offset:5288
	ds_write_b32 v3, v71 offset:5292
	ds_write_b32 v3, v72 offset:6336
	ds_write_b32 v3, v73 offset:6340
	ds_write_b32 v3, v74 offset:6344
	ds_write_b32 v3, v75 offset:6348
	ds_write_b32 v3, v76 offset:7392
	ds_write_b32 v3, v77 offset:7396
	ds_write_b32 v3, v78 offset:7400
	ds_write_b32 v3, v79 offset:7404
	s_waitcnt lgkmcnt(0)
	s_add_i32 s3, s0, 5120
	s_mul_i32 s29, s3, 0x1745e
	s_lshr_b32 s29, s29, 25
	s_mul_i32 s35, s29, 0x160
	s_sub_i32 s35, s3, s35
	s_lshl_b32 s58, s35, 17
	s_lshl_b32 s59, s29, 7
	s_add_u32 s58, s58, s59
	s_add_u32 s48, s42, s58
	s_addc_u32 s49, s43, 0
	ds_read2_b32 v[8:9], v4 offset0:0 offset1:33
	ds_read2_b32 v[10:11], v4 offset0:66 offset1:99
	ds_read2_b32 v[12:13], v4 offset0:132 offset1:165
	ds_read2_b32 v[14:15], v4 offset0:198 offset1:231
	s_waitcnt lgkmcnt(0)
	v_cvt_pk_bf16_f32 v48, v8, v9
	v_cvt_pk_bf16_f32 v49, v10, v11
	v_cvt_pk_bf16_f32 v50, v12, v13
	v_cvt_pk_bf16_f32 v51, v14, v15
	global_store_dwordx4 v6, v[48:51], s[48:49]
	ds_read2_b32 v[8:9], v4 offset0:8 offset1:41
	ds_read2_b32 v[10:11], v4 offset0:74 offset1:107
	ds_read2_b32 v[12:13], v4 offset0:140 offset1:173
	ds_read2_b32 v[14:15], v4 offset0:206 offset1:239
	s_waitcnt lgkmcnt(0)
	v_cvt_pk_bf16_f32 v52, v8, v9
	v_cvt_pk_bf16_f32 v53, v10, v11
	v_cvt_pk_bf16_f32 v54, v12, v13
	v_cvt_pk_bf16_f32 v55, v14, v15
	v_add_u32_e32 v7, 0x8000, v6
	global_store_dwordx4 v7, v[52:55], s[48:49]
	ds_read2_b32 v[8:9], v4 offset0:16 offset1:49
	ds_read2_b32 v[10:11], v4 offset0:82 offset1:115
	ds_read2_b32 v[12:13], v4 offset0:148 offset1:181
	ds_read2_b32 v[14:15], v4 offset0:214 offset1:247
	s_waitcnt lgkmcnt(0)
	v_cvt_pk_bf16_f32 v56, v8, v9
	v_cvt_pk_bf16_f32 v57, v10, v11
	v_cvt_pk_bf16_f32 v58, v12, v13
	v_cvt_pk_bf16_f32 v59, v14, v15
	v_add_u32_e32 v7, 0x10000, v6
	global_store_dwordx4 v7, v[56:59], s[48:49]
	ds_read2_b32 v[8:9], v4 offset0:24 offset1:57
	ds_read2_b32 v[10:11], v4 offset0:90 offset1:123
	ds_read2_b32 v[12:13], v4 offset0:156 offset1:189
	ds_read2_b32 v[14:15], v4 offset0:222 offset1:255
	s_waitcnt lgkmcnt(0)
	v_cvt_pk_bf16_f32 v60, v8, v9
	v_cvt_pk_bf16_f32 v61, v10, v11
	v_cvt_pk_bf16_f32 v62, v12, v13
	v_cvt_pk_bf16_f32 v63, v14, v15
	v_add_u32_e32 v7, 0x18000, v6
	global_store_dwordx4 v7, v[60:63], s[48:49]
	s_add_i32 s3, s0, 8192
	s_mul_i32 s29, s3, 0x1745e
	s_lshr_b32 s29, s29, 25
	s_mul_i32 s35, s29, 0x160
	s_sub_i32 s35, s3, s35
	s_mul_i32 s58, s29, 0x2c0000
	s_lshl_b32 s59, s35, 7
	s_add_u32 s58, s58, s59
	s_add_u32 s46, s10, s58
	s_addc_u32 s47, s11, 0
	global_load_dwordx4 v[48:51], v2, s[46:47] nt
	v_add_u32_e32 v7, 0x58000, v2
	global_load_dwordx4 v[52:55], v7, s[46:47] nt
	v_add_u32_e32 v7, 0xb0000, v2
	global_load_dwordx4 v[56:59], v7, s[46:47] nt
	v_add_u32_e32 v7, 0x108000, v2
	global_load_dwordx4 v[60:63], v7, s[46:47] nt
	v_add_u32_e32 v7, 0x160000, v2
	global_load_dwordx4 v[64:67], v7, s[46:47] nt
	v_add_u32_e32 v7, 0x1b8000, v2
	global_load_dwordx4 v[68:71], v7, s[46:47] nt
	v_add_u32_e32 v7, 0x210000, v2
	global_load_dwordx4 v[72:75], v7, s[46:47] nt
	v_add_u32_e32 v7, 0x268000, v2
	global_load_dwordx4 v[76:79], v7, s[46:47] nt
	s_waitcnt vmcnt(24)
	ds_write_b32 v3, v80
	ds_write_b32 v3, v81 offset:4
	ds_write_b32 v3, v82 offset:8
	ds_write_b32 v3, v83 offset:12
	ds_write_b32 v3, v84 offset:1056
	ds_write_b32 v3, v85 offset:1060
	ds_write_b32 v3, v86 offset:1064
	ds_write_b32 v3, v87 offset:1068
	ds_write_b32 v3, v88 offset:2112
	ds_write_b32 v3, v89 offset:2116
	ds_write_b32 v3, v90 offset:2120
	ds_write_b32 v3, v91 offset:2124
	ds_write_b32 v3, v92 offset:3168
	ds_write_b32 v3, v93 offset:3172
	ds_write_b32 v3, v94 offset:3176
	ds_write_b32 v3, v95 offset:3180
	ds_write_b32 v3, v96 offset:4224
	ds_write_b32 v3, v97 offset:4228
	ds_write_b32 v3, v98 offset:4232
	ds_write_b32 v3, v99 offset:4236
	ds_write_b32 v3, v100 offset:5280
	ds_write_b32 v3, v101 offset:5284
	ds_write_b32 v3, v102 offset:5288
	ds_write_b32 v3, v103 offset:5292
	ds_write_b32 v3, v104 offset:6336
	ds_write_b32 v3, v105 offset:6340
	ds_write_b32 v3, v106 offset:6344
	ds_write_b32 v3, v107 offset:6348
	ds_write_b32 v3, v108 offset:7392
	ds_write_b32 v3, v109 offset:7396
	ds_write_b32 v3, v110 offset:7400
	ds_write_b32 v3, v111 offset:7404
	s_waitcnt lgkmcnt(0)
	s_add_i32 s3, s0, 6144
	s_mul_i32 s29, s3, 0x1745e
	s_lshr_b32 s29, s29, 25
	s_mul_i32 s35, s29, 0x160
	s_sub_i32 s35, s3, s35
	s_lshl_b32 s58, s35, 17
	s_lshl_b32 s59, s29, 7
	s_add_u32 s58, s58, s59
	s_add_u32 s48, s42, s58
	s_addc_u32 s49, s43, 0
	ds_read2_b32 v[8:9], v4 offset0:0 offset1:33
	ds_read2_b32 v[10:11], v4 offset0:66 offset1:99
	ds_read2_b32 v[12:13], v4 offset0:132 offset1:165
	ds_read2_b32 v[14:15], v4 offset0:198 offset1:231
	s_waitcnt lgkmcnt(0)
	v_cvt_pk_bf16_f32 v80, v8, v9
	v_cvt_pk_bf16_f32 v81, v10, v11
	v_cvt_pk_bf16_f32 v82, v12, v13
	v_cvt_pk_bf16_f32 v83, v14, v15
	global_store_dwordx4 v6, v[80:83], s[48:49]
	ds_read2_b32 v[8:9], v4 offset0:8 offset1:41
	ds_read2_b32 v[10:11], v4 offset0:74 offset1:107
	ds_read2_b32 v[12:13], v4 offset0:140 offset1:173
	ds_read2_b32 v[14:15], v4 offset0:206 offset1:239
	s_waitcnt lgkmcnt(0)
	v_cvt_pk_bf16_f32 v84, v8, v9
	v_cvt_pk_bf16_f32 v85, v10, v11
	v_cvt_pk_bf16_f32 v86, v12, v13
	v_cvt_pk_bf16_f32 v87, v14, v15
	v_add_u32_e32 v7, 0x8000, v6
	global_store_dwordx4 v7, v[84:87], s[48:49]
	ds_read2_b32 v[8:9], v4 offset0:16 offset1:49
	ds_read2_b32 v[10:11], v4 offset0:82 offset1:115
	ds_read2_b32 v[12:13], v4 offset0:148 offset1:181
	ds_read2_b32 v[14:15], v4 offset0:214 offset1:247
	s_waitcnt lgkmcnt(0)
	v_cvt_pk_bf16_f32 v88, v8, v9
	v_cvt_pk_bf16_f32 v89, v10, v11
	v_cvt_pk_bf16_f32 v90, v12, v13
	v_cvt_pk_bf16_f32 v91, v14, v15
	v_add_u32_e32 v7, 0x10000, v6
	global_store_dwordx4 v7, v[88:91], s[48:49]
	ds_read2_b32 v[8:9], v4 offset0:24 offset1:57
	ds_read2_b32 v[10:11], v4 offset0:90 offset1:123
	ds_read2_b32 v[12:13], v4 offset0:156 offset1:189
	ds_read2_b32 v[14:15], v4 offset0:222 offset1:255
	s_waitcnt lgkmcnt(0)
	v_cvt_pk_bf16_f32 v92, v8, v9
	v_cvt_pk_bf16_f32 v93, v10, v11
	v_cvt_pk_bf16_f32 v94, v12, v13
	v_cvt_pk_bf16_f32 v95, v14, v15
	v_add_u32_e32 v7, 0x18000, v6
	global_store_dwordx4 v7, v[92:95], s[48:49]
	s_add_i32 s3, s0, 9216
	s_mul_i32 s29, s3, 0x1745e
	s_lshr_b32 s29, s29, 25
	s_mul_i32 s35, s29, 0x160
	s_sub_i32 s35, s3, s35
	s_mul_i32 s58, s29, 0x2c0000
	s_lshl_b32 s59, s35, 7
	s_add_u32 s58, s58, s59
	s_add_u32 s46, s10, s58
	s_addc_u32 s47, s11, 0
	global_load_dwordx4 v[80:83], v2, s[46:47] nt
	v_add_u32_e32 v7, 0x58000, v2
	global_load_dwordx4 v[84:87], v7, s[46:47] nt
	v_add_u32_e32 v7, 0xb0000, v2
	global_load_dwordx4 v[88:91], v7, s[46:47] nt
	v_add_u32_e32 v7, 0x108000, v2
	global_load_dwordx4 v[92:95], v7, s[46:47] nt
	v_add_u32_e32 v7, 0x160000, v2
	global_load_dwordx4 v[96:99], v7, s[46:47] nt
	v_add_u32_e32 v7, 0x1b8000, v2
	global_load_dwordx4 v[100:103], v7, s[46:47] nt
	v_add_u32_e32 v7, 0x210000, v2
	global_load_dwordx4 v[104:107], v7, s[46:47] nt
	v_add_u32_e32 v7, 0x268000, v2
	global_load_dwordx4 v[108:111], v7, s[46:47] nt
	s_waitcnt vmcnt(24)
	ds_write_b32 v3, v16
	ds_write_b32 v3, v17 offset:4
	ds_write_b32 v3, v18 offset:8
	ds_write_b32 v3, v19 offset:12
	ds_write_b32 v3, v20 offset:1056
	ds_write_b32 v3, v21 offset:1060
	ds_write_b32 v3, v22 offset:1064
	ds_write_b32 v3, v23 offset:1068
	ds_write_b32 v3, v24 offset:2112
	ds_write_b32 v3, v25 offset:2116
	ds_write_b32 v3, v26 offset:2120
	ds_write_b32 v3, v27 offset:2124
	ds_write_b32 v3, v28 offset:3168
	ds_write_b32 v3, v29 offset:3172
	ds_write_b32 v3, v30 offset:3176
	ds_write_b32 v3, v31 offset:3180
	ds_write_b32 v3, v32 offset:4224
	ds_write_b32 v3, v33 offset:4228
	ds_write_b32 v3, v34 offset:4232
	ds_write_b32 v3, v35 offset:4236
	ds_write_b32 v3, v36 offset:5280
	ds_write_b32 v3, v37 offset:5284
	ds_write_b32 v3, v38 offset:5288
	ds_write_b32 v3, v39 offset:5292
	ds_write_b32 v3, v40 offset:6336
	ds_write_b32 v3, v41 offset:6340
	ds_write_b32 v3, v42 offset:6344
	ds_write_b32 v3, v43 offset:6348
	ds_write_b32 v3, v44 offset:7392
	ds_write_b32 v3, v45 offset:7396
	ds_write_b32 v3, v46 offset:7400
	ds_write_b32 v3, v47 offset:7404
	s_waitcnt lgkmcnt(0)
	s_add_i32 s3, s0, 7168
	s_mul_i32 s29, s3, 0x1745e
	s_lshr_b32 s29, s29, 25
	s_mul_i32 s35, s29, 0x160
	s_sub_i32 s35, s3, s35
	s_lshl_b32 s58, s35, 17
	s_lshl_b32 s59, s29, 7
	s_add_u32 s58, s58, s59
	s_add_u32 s48, s42, s58
	s_addc_u32 s49, s43, 0
	ds_read2_b32 v[8:9], v4 offset0:0 offset1:33
	ds_read2_b32 v[10:11], v4 offset0:66 offset1:99
	ds_read2_b32 v[12:13], v4 offset0:132 offset1:165
	ds_read2_b32 v[14:15], v4 offset0:198 offset1:231
	s_waitcnt lgkmcnt(0)
	v_cvt_pk_bf16_f32 v16, v8, v9
	v_cvt_pk_bf16_f32 v17, v10, v11
	v_cvt_pk_bf16_f32 v18, v12, v13
	v_cvt_pk_bf16_f32 v19, v14, v15
	global_store_dwordx4 v6, v[16:19], s[48:49]
	ds_read2_b32 v[8:9], v4 offset0:8 offset1:41
	ds_read2_b32 v[10:11], v4 offset0:74 offset1:107
	ds_read2_b32 v[12:13], v4 offset0:140 offset1:173
	ds_read2_b32 v[14:15], v4 offset0:206 offset1:239
	s_waitcnt lgkmcnt(0)
	v_cvt_pk_bf16_f32 v20, v8, v9
	v_cvt_pk_bf16_f32 v21, v10, v11
	v_cvt_pk_bf16_f32 v22, v12, v13
	v_cvt_pk_bf16_f32 v23, v14, v15
	v_add_u32_e32 v7, 0x8000, v6
	global_store_dwordx4 v7, v[20:23], s[48:49]
	ds_read2_b32 v[8:9], v4 offset0:16 offset1:49
	ds_read2_b32 v[10:11], v4 offset0:82 offset1:115
	ds_read2_b32 v[12:13], v4 offset0:148 offset1:181
	ds_read2_b32 v[14:15], v4 offset0:214 offset1:247
	s_waitcnt lgkmcnt(0)
	v_cvt_pk_bf16_f32 v24, v8, v9
	v_cvt_pk_bf16_f32 v25, v10, v11
	v_cvt_pk_bf16_f32 v26, v12, v13
	v_cvt_pk_bf16_f32 v27, v14, v15
	v_add_u32_e32 v7, 0x10000, v6
	global_store_dwordx4 v7, v[24:27], s[48:49]
	ds_read2_b32 v[8:9], v4 offset0:24 offset1:57
	ds_read2_b32 v[10:11], v4 offset0:90 offset1:123
	ds_read2_b32 v[12:13], v4 offset0:156 offset1:189
	ds_read2_b32 v[14:15], v4 offset0:222 offset1:255
	s_waitcnt lgkmcnt(0)
	v_cvt_pk_bf16_f32 v28, v8, v9
	v_cvt_pk_bf16_f32 v29, v10, v11
	v_cvt_pk_bf16_f32 v30, v12, v13
	v_cvt_pk_bf16_f32 v31, v14, v15
	v_add_u32_e32 v7, 0x18000, v6
	global_store_dwordx4 v7, v[28:31], s[48:49]
	s_add_i32 s3, s0, 10240
	s_mul_i32 s29, s3, 0x1745e
	s_lshr_b32 s29, s29, 25
	s_mul_i32 s35, s29, 0x160
	s_sub_i32 s35, s3, s35
	s_mul_i32 s58, s29, 0x2c0000
	s_lshl_b32 s59, s35, 7
	s_add_u32 s58, s58, s59
	s_add_u32 s46, s10, s58
	s_addc_u32 s47, s11, 0
	global_load_dwordx4 v[16:19], v2, s[46:47] nt
	v_add_u32_e32 v7, 0x58000, v2
	global_load_dwordx4 v[20:23], v7, s[46:47] nt
	v_add_u32_e32 v7, 0xb0000, v2
	global_load_dwordx4 v[24:27], v7, s[46:47] nt
	v_add_u32_e32 v7, 0x108000, v2
	global_load_dwordx4 v[28:31], v7, s[46:47] nt
	v_add_u32_e32 v7, 0x160000, v2
	global_load_dwordx4 v[32:35], v7, s[46:47] nt
	v_add_u32_e32 v7, 0x1b8000, v2
	global_load_dwordx4 v[36:39], v7, s[46:47] nt
	v_add_u32_e32 v7, 0x210000, v2
	global_load_dwordx4 v[40:43], v7, s[46:47] nt
	v_add_u32_e32 v7, 0x268000, v2
	global_load_dwordx4 v[44:47], v7, s[46:47] nt
	s_waitcnt vmcnt(24)
	ds_write_b32 v3, v48
	ds_write_b32 v3, v49 offset:4
	ds_write_b32 v3, v50 offset:8
	ds_write_b32 v3, v51 offset:12
	ds_write_b32 v3, v52 offset:1056
	ds_write_b32 v3, v53 offset:1060
	ds_write_b32 v3, v54 offset:1064
	ds_write_b32 v3, v55 offset:1068
	ds_write_b32 v3, v56 offset:2112
	ds_write_b32 v3, v57 offset:2116
	ds_write_b32 v3, v58 offset:2120
	ds_write_b32 v3, v59 offset:2124
	ds_write_b32 v3, v60 offset:3168
	ds_write_b32 v3, v61 offset:3172
	ds_write_b32 v3, v62 offset:3176
	ds_write_b32 v3, v63 offset:3180
	ds_write_b32 v3, v64 offset:4224
	ds_write_b32 v3, v65 offset:4228
	ds_write_b32 v3, v66 offset:4232
	ds_write_b32 v3, v67 offset:4236
	ds_write_b32 v3, v68 offset:5280
	ds_write_b32 v3, v69 offset:5284
	ds_write_b32 v3, v70 offset:5288
	ds_write_b32 v3, v71 offset:5292
	ds_write_b32 v3, v72 offset:6336
	ds_write_b32 v3, v73 offset:6340
	ds_write_b32 v3, v74 offset:6344
	ds_write_b32 v3, v75 offset:6348
	ds_write_b32 v3, v76 offset:7392
	ds_write_b32 v3, v77 offset:7396
	ds_write_b32 v3, v78 offset:7400
	ds_write_b32 v3, v79 offset:7404
	s_waitcnt lgkmcnt(0)
	s_add_i32 s3, s0, 8192
	s_mul_i32 s29, s3, 0x1745e
	s_lshr_b32 s29, s29, 25
	s_mul_i32 s35, s29, 0x160
	s_sub_i32 s35, s3, s35
	s_lshl_b32 s58, s35, 17
	s_lshl_b32 s59, s29, 7
	s_add_u32 s58, s58, s59
	s_add_u32 s48, s42, s58
	s_addc_u32 s49, s43, 0
	ds_read2_b32 v[8:9], v4 offset0:0 offset1:33
	ds_read2_b32 v[10:11], v4 offset0:66 offset1:99
	ds_read2_b32 v[12:13], v4 offset0:132 offset1:165
	ds_read2_b32 v[14:15], v4 offset0:198 offset1:231
	s_waitcnt lgkmcnt(0)
	v_cvt_pk_bf16_f32 v48, v8, v9
	v_cvt_pk_bf16_f32 v49, v10, v11
	v_cvt_pk_bf16_f32 v50, v12, v13
	v_cvt_pk_bf16_f32 v51, v14, v15
	global_store_dwordx4 v6, v[48:51], s[48:49]
	ds_read2_b32 v[8:9], v4 offset0:8 offset1:41
	ds_read2_b32 v[10:11], v4 offset0:74 offset1:107
	ds_read2_b32 v[12:13], v4 offset0:140 offset1:173
	ds_read2_b32 v[14:15], v4 offset0:206 offset1:239
	s_waitcnt lgkmcnt(0)
	v_cvt_pk_bf16_f32 v52, v8, v9
	v_cvt_pk_bf16_f32 v53, v10, v11
	v_cvt_pk_bf16_f32 v54, v12, v13
	v_cvt_pk_bf16_f32 v55, v14, v15
	v_add_u32_e32 v7, 0x8000, v6
	global_store_dwordx4 v7, v[52:55], s[48:49]
	ds_read2_b32 v[8:9], v4 offset0:16 offset1:49
	ds_read2_b32 v[10:11], v4 offset0:82 offset1:115
	ds_read2_b32 v[12:13], v4 offset0:148 offset1:181
	ds_read2_b32 v[14:15], v4 offset0:214 offset1:247
	s_waitcnt lgkmcnt(0)
	v_cvt_pk_bf16_f32 v56, v8, v9
	v_cvt_pk_bf16_f32 v57, v10, v11
	v_cvt_pk_bf16_f32 v58, v12, v13
	v_cvt_pk_bf16_f32 v59, v14, v15
	v_add_u32_e32 v7, 0x10000, v6
	global_store_dwordx4 v7, v[56:59], s[48:49]
	ds_read2_b32 v[8:9], v4 offset0:24 offset1:57
	ds_read2_b32 v[10:11], v4 offset0:90 offset1:123
	ds_read2_b32 v[12:13], v4 offset0:156 offset1:189
	ds_read2_b32 v[14:15], v4 offset0:222 offset1:255
	s_waitcnt lgkmcnt(0)
	v_cvt_pk_bf16_f32 v60, v8, v9
	v_cvt_pk_bf16_f32 v61, v10, v11
	v_cvt_pk_bf16_f32 v62, v12, v13
	v_cvt_pk_bf16_f32 v63, v14, v15
	v_add_u32_e32 v7, 0x18000, v6
	global_store_dwordx4 v7, v[60:63], s[48:49]
	s_waitcnt vmcnt(16)
	ds_write_b32 v3, v80
	ds_write_b32 v3, v81 offset:4
	ds_write_b32 v3, v82 offset:8
	ds_write_b32 v3, v83 offset:12
	ds_write_b32 v3, v84 offset:1056
	ds_write_b32 v3, v85 offset:1060
	ds_write_b32 v3, v86 offset:1064
	ds_write_b32 v3, v87 offset:1068
	ds_write_b32 v3, v88 offset:2112
	ds_write_b32 v3, v89 offset:2116
	ds_write_b32 v3, v90 offset:2120
	ds_write_b32 v3, v91 offset:2124
	ds_write_b32 v3, v92 offset:3168
	ds_write_b32 v3, v93 offset:3172
	ds_write_b32 v3, v94 offset:3176
	ds_write_b32 v3, v95 offset:3180
	ds_write_b32 v3, v96 offset:4224
	ds_write_b32 v3, v97 offset:4228
	ds_write_b32 v3, v98 offset:4232
	ds_write_b32 v3, v99 offset:4236
	ds_write_b32 v3, v100 offset:5280
	ds_write_b32 v3, v101 offset:5284
	ds_write_b32 v3, v102 offset:5288
	ds_write_b32 v3, v103 offset:5292
	ds_write_b32 v3, v104 offset:6336
	ds_write_b32 v3, v105 offset:6340
	ds_write_b32 v3, v106 offset:6344
	ds_write_b32 v3, v107 offset:6348
	ds_write_b32 v3, v108 offset:7392
	ds_write_b32 v3, v109 offset:7396
	ds_write_b32 v3, v110 offset:7400
	ds_write_b32 v3, v111 offset:7404
	s_waitcnt lgkmcnt(0)
	s_add_i32 s3, s0, 9216
	s_mul_i32 s29, s3, 0x1745e
	s_lshr_b32 s29, s29, 25
	s_mul_i32 s35, s29, 0x160
	s_sub_i32 s35, s3, s35
	s_lshl_b32 s58, s35, 17
	s_lshl_b32 s59, s29, 7
	s_add_u32 s58, s58, s59
	s_add_u32 s48, s42, s58
	s_addc_u32 s49, s43, 0
	ds_read2_b32 v[8:9], v4 offset0:0 offset1:33
	ds_read2_b32 v[10:11], v4 offset0:66 offset1:99
	ds_read2_b32 v[12:13], v4 offset0:132 offset1:165
	ds_read2_b32 v[14:15], v4 offset0:198 offset1:231
	s_waitcnt lgkmcnt(0)
	v_cvt_pk_bf16_f32 v80, v8, v9
	v_cvt_pk_bf16_f32 v81, v10, v11
	v_cvt_pk_bf16_f32 v82, v12, v13
	v_cvt_pk_bf16_f32 v83, v14, v15
	global_store_dwordx4 v6, v[80:83], s[48:49]
	ds_read2_b32 v[8:9], v4 offset0:8 offset1:41
	ds_read2_b32 v[10:11], v4 offset0:74 offset1:107
	ds_read2_b32 v[12:13], v4 offset0:140 offset1:173
	ds_read2_b32 v[14:15], v4 offset0:206 offset1:239
	s_waitcnt lgkmcnt(0)
	v_cvt_pk_bf16_f32 v84, v8, v9
	v_cvt_pk_bf16_f32 v85, v10, v11
	v_cvt_pk_bf16_f32 v86, v12, v13
	v_cvt_pk_bf16_f32 v87, v14, v15
	v_add_u32_e32 v7, 0x8000, v6
	global_store_dwordx4 v7, v[84:87], s[48:49]
	ds_read2_b32 v[8:9], v4 offset0:16 offset1:49
	ds_read2_b32 v[10:11], v4 offset0:82 offset1:115
	ds_read2_b32 v[12:13], v4 offset0:148 offset1:181
	ds_read2_b32 v[14:15], v4 offset0:214 offset1:247
	s_waitcnt lgkmcnt(0)
	v_cvt_pk_bf16_f32 v88, v8, v9
	v_cvt_pk_bf16_f32 v89, v10, v11
	v_cvt_pk_bf16_f32 v90, v12, v13
	v_cvt_pk_bf16_f32 v91, v14, v15
	v_add_u32_e32 v7, 0x10000, v6
	global_store_dwordx4 v7, v[88:91], s[48:49]
	ds_read2_b32 v[8:9], v4 offset0:24 offset1:57
	ds_read2_b32 v[10:11], v4 offset0:90 offset1:123
	ds_read2_b32 v[12:13], v4 offset0:156 offset1:189
	ds_read2_b32 v[14:15], v4 offset0:222 offset1:255
	s_waitcnt lgkmcnt(0)
	v_cvt_pk_bf16_f32 v92, v8, v9
	v_cvt_pk_bf16_f32 v93, v10, v11
	v_cvt_pk_bf16_f32 v94, v12, v13
	v_cvt_pk_bf16_f32 v95, v14, v15
	v_add_u32_e32 v7, 0x18000, v6
	global_store_dwordx4 v7, v[92:95], s[48:49]
	s_waitcnt vmcnt(8)
	ds_write_b32 v3, v16
	ds_write_b32 v3, v17 offset:4
	ds_write_b32 v3, v18 offset:8
	ds_write_b32 v3, v19 offset:12
	ds_write_b32 v3, v20 offset:1056
	ds_write_b32 v3, v21 offset:1060
	ds_write_b32 v3, v22 offset:1064
	ds_write_b32 v3, v23 offset:1068
	ds_write_b32 v3, v24 offset:2112
	ds_write_b32 v3, v25 offset:2116
	ds_write_b32 v3, v26 offset:2120
	ds_write_b32 v3, v27 offset:2124
	ds_write_b32 v3, v28 offset:3168
	ds_write_b32 v3, v29 offset:3172
	ds_write_b32 v3, v30 offset:3176
	ds_write_b32 v3, v31 offset:3180
	ds_write_b32 v3, v32 offset:4224
	ds_write_b32 v3, v33 offset:4228
	ds_write_b32 v3, v34 offset:4232
	ds_write_b32 v3, v35 offset:4236
	ds_write_b32 v3, v36 offset:5280
	ds_write_b32 v3, v37 offset:5284
	ds_write_b32 v3, v38 offset:5288
	ds_write_b32 v3, v39 offset:5292
	ds_write_b32 v3, v40 offset:6336
	ds_write_b32 v3, v41 offset:6340
	ds_write_b32 v3, v42 offset:6344
	ds_write_b32 v3, v43 offset:6348
	ds_write_b32 v3, v44 offset:7392
	ds_write_b32 v3, v45 offset:7396
	ds_write_b32 v3, v46 offset:7400
	ds_write_b32 v3, v47 offset:7404
	s_waitcnt lgkmcnt(0)
	s_add_i32 s3, s0, 10240
	s_mul_i32 s29, s3, 0x1745e
	s_lshr_b32 s29, s29, 25
	s_mul_i32 s35, s29, 0x160
	s_sub_i32 s35, s3, s35
	s_lshl_b32 s58, s35, 17
	s_lshl_b32 s59, s29, 7
	s_add_u32 s58, s58, s59
	s_add_u32 s48, s42, s58
	s_addc_u32 s49, s43, 0
	ds_read2_b32 v[8:9], v4 offset0:0 offset1:33
	ds_read2_b32 v[10:11], v4 offset0:66 offset1:99
	ds_read2_b32 v[12:13], v4 offset0:132 offset1:165
	ds_read2_b32 v[14:15], v4 offset0:198 offset1:231
	s_waitcnt lgkmcnt(0)
	v_cvt_pk_bf16_f32 v16, v8, v9
	v_cvt_pk_bf16_f32 v17, v10, v11
	v_cvt_pk_bf16_f32 v18, v12, v13
	v_cvt_pk_bf16_f32 v19, v14, v15
	global_store_dwordx4 v6, v[16:19], s[48:49]
	ds_read2_b32 v[8:9], v4 offset0:8 offset1:41
	ds_read2_b32 v[10:11], v4 offset0:74 offset1:107
	ds_read2_b32 v[12:13], v4 offset0:140 offset1:173
	ds_read2_b32 v[14:15], v4 offset0:206 offset1:239
	s_waitcnt lgkmcnt(0)
	v_cvt_pk_bf16_f32 v20, v8, v9
	v_cvt_pk_bf16_f32 v21, v10, v11
	v_cvt_pk_bf16_f32 v22, v12, v13
	v_cvt_pk_bf16_f32 v23, v14, v15
	v_add_u32_e32 v7, 0x8000, v6
	global_store_dwordx4 v7, v[20:23], s[48:49]
	ds_read2_b32 v[8:9], v4 offset0:16 offset1:49
	ds_read2_b32 v[10:11], v4 offset0:82 offset1:115
	ds_read2_b32 v[12:13], v4 offset0:148 offset1:181
	ds_read2_b32 v[14:15], v4 offset0:214 offset1:247
	s_waitcnt lgkmcnt(0)
	v_cvt_pk_bf16_f32 v24, v8, v9
	v_cvt_pk_bf16_f32 v25, v10, v11
	v_cvt_pk_bf16_f32 v26, v12, v13
	v_cvt_pk_bf16_f32 v27, v14, v15
	v_add_u32_e32 v7, 0x10000, v6
	global_store_dwordx4 v7, v[24:27], s[48:49]
	ds_read2_b32 v[8:9], v4 offset0:24 offset1:57
	ds_read2_b32 v[10:11], v4 offset0:90 offset1:123
	ds_read2_b32 v[12:13], v4 offset0:156 offset1:189
	ds_read2_b32 v[14:15], v4 offset0:222 offset1:255
	s_waitcnt lgkmcnt(0)
	v_cvt_pk_bf16_f32 v28, v8, v9
	v_cvt_pk_bf16_f32 v29, v10, v11
	v_cvt_pk_bf16_f32 v30, v12, v13
	v_cvt_pk_bf16_f32 v31, v14, v15
	v_add_u32_e32 v7, 0x18000, v6
	global_store_dwordx4 v7, v[28:31], s[48:49]
